# all attention loops: v_pk_add_f32 split into scalar v_add_f32 pairs (136 sites, bit-identical sums)
# baseline (speedup 1.0000x reference)
; DI float ex2(float x) { return __builtin_amdgcn_exp2f(x); }
; #define MFMA32(a, b, c) __builtin_amdgcn_mfma_f32_32x32x16_bf16((a), (b), (c), 0, 0, 0)
; DI void mla_item(const P& p, char* smem, int b, int hd, int q0, bool samp) {
;     ...
;       f32x16 s[2];
;       const float cinit = (kb == 0) ? 0.f : -mrun;
; #pragma unroll
;       for (int i = 0; i < 16; ++i) { s[0][i] = cinit; s[1][i] = cinit; }
;       const char* kp = Kt + l32 * KS_MLA + lh * 16;
; #pragma unroll
;       for (int ks = 0; ks < 6; ++ks) {
;         const bf16x8 a0 = *(const bf16x8*)(kp + ks * 32);
;         const bf16x8 a1 = *(const bf16x8*)(kp + 32 * KS_MLA + ks * 32);
;         s[0] = MFMA32(a0, qf[ks], s[0]);
;         s[1] = MFMA32(a1, qf[ks], s[1]);
;       }
;       f32x16 e[2];
;       float ps0 = 0.f, ps1 = 0.f;
;       bool redo = (kb == 0);
;       if (!redo) {
; #pragma unroll
;         for (int i = 0; i < 16; ++i) { e[0][i] = ex2(s[0][i]); e[1][i] = ex2(s[1][i]); ps0 += e[0][i]; ps1 += e[1][i]; }
;         redo = (__builtin_amdgcn_ballot_w64(!(ps0 + ps1 < 1e18f)) != 0ull);
;       }
;       if (redo) {
;         float mx = fmaxf(s[0][0], s[1][0]);
; #pragma unroll
;         for (int i = 1; i < 16; ++i) mx = fmaxf(mx, fmaxf(s[0][i], s[1][i]));
;         mx = fmaxf(mx, __shfl_xor(mx, 32));
.LBB0_402:
	s_or_b64 exec, exec, s[6:7]
	v_and_b32_e32 v4, 3, v4
	v_lshrrev_b32_e32 v5, 3, v1
	v_and_b32_e32 v2, 63, v1
	v_and_or_b32 v4, v5, 4, v4
	v_mul_u32_u24_e32 v107, 0xc0, v4
	v_lshlrev_b32_e32 v4, 1, v2
	v_lshlrev_b32_e32 v2, 3, v2
	v_mul_u32_u24_e32 v160, 0xd0, v14
	v_and_b32_e32 v147, 32, v4
	s_cmpk_lt_i32 s61, 0xffc1
	v_and_b32_e32 v148, 24, v2
	s_cbranch_scc1 .LBB0_404
	v_add3_u32 v2, 16, v160, v106
	ds_read_b128 v[4:7], v2
	ds_read_b128 v[52:55], v2 offset:32
	ds_read_b128 v[20:23], v2 offset:6656
	ds_read_b128 v[56:59], v2 offset:6688
	s_waitcnt lgkmcnt(3)
	v_mfma_f32_32x32x16_bf16 v[4:19], v[4:7], v[88:91], 0
	s_waitcnt lgkmcnt(1)
	v_mfma_f32_32x32x16_bf16 v[20:35], v[20:23], v[88:91], 0
	v_mfma_f32_32x32x16_bf16 v[4:19], v[52:55], v[84:87], v[4:19]
	s_waitcnt lgkmcnt(0)
	v_mfma_f32_32x32x16_bf16 v[20:35], v[56:59], v[84:87], v[20:35]
	ds_read_b128 v[52:55], v2 offset:64
	ds_read_b128 v[56:59], v2 offset:96
	s_waitcnt lgkmcnt(1)
	v_mfma_f32_32x32x16_bf16 v[4:19], v[52:55], v[80:83], v[4:19]
	ds_read_b128 v[52:55], v2 offset:6720
	ds_read_b128 v[60:63], v2 offset:6752
	s_waitcnt lgkmcnt(1)
	v_mfma_f32_32x32x16_bf16 v[20:35], v[52:55], v[80:83], v[20:35]
	v_mfma_f32_32x32x16_bf16 v[4:19], v[56:59], v[76:79], v[4:19]
	ds_read_b128 v[52:55], v2 offset:128
	ds_read_b128 v[56:59], v2 offset:160
	s_waitcnt lgkmcnt(2)
	v_mfma_f32_32x32x16_bf16 v[20:35], v[60:63], v[76:79], v[20:35]
	s_waitcnt lgkmcnt(1)
	v_mfma_f32_32x32x16_bf16 v[4:19], v[52:55], v[72:75], v[4:19]
	ds_read_b128 v[52:55], v2 offset:6784
	ds_read_b128 v[60:63], v2 offset:6816
	s_waitcnt lgkmcnt(1)
	v_mfma_f32_32x32x16_bf16 v[20:35], v[52:55], v[72:75], v[20:35]
	s_waitcnt lgkmcnt(0)
	v_mfma_f32_32x32x16_bf16 v[20:35], v[60:63], v[68:71], v[20:35]
	v_mfma_f32_32x32x16_bf16 v[4:19], v[56:59], v[68:71], v[4:19]
	s_nop 10
	v_max_f32_e32 v2, v21, v21
	v_max_f32_e32 v51, v5, v5
	v_max_f32_e32 v2, v51, v2
	v_max_f32_e32 v51, v22, v22
	v_max_f32_e32 v52, v6, v6
	v_max_f32_e32 v51, v52, v51
	v_max_f32_e32 v52, v23, v23
	v_max_f32_e32 v53, v7, v7
	v_max3_f32 v2, v4, v20, v2
	v_max_f32_e32 v52, v53, v52
	v_max3_f32 v2, v2, v51, v52
	v_max_f32_e32 v51, v24, v24
	v_max_f32_e32 v52, v8, v8
	v_max_f32_e32 v51, v52, v51
	v_max_f32_e32 v52, v25, v25
	v_max_f32_e32 v53, v9, v9
	v_max_f32_e32 v52, v53, v52
	v_max3_f32 v2, v2, v51, v52
	v_max_f32_e32 v51, v26, v26
	v_max_f32_e32 v52, v10, v10
	v_max_f32_e32 v51, v52, v51
	v_max_f32_e32 v52, v27, v27
	v_max_f32_e32 v53, v11, v11
	v_max_f32_e32 v52, v53, v52
	v_max3_f32 v2, v2, v51, v52
	v_max_f32_e32 v51, v28, v28
	v_max_f32_e32 v52, v12, v12
	v_max_f32_e32 v51, v52, v51
	v_max_f32_e32 v52, v29, v29
	v_max_f32_e32 v53, v13, v13
	v_max_f32_e32 v52, v53, v52
	v_max3_f32 v2, v2, v51, v52
	v_max_f32_e32 v51, v30, v30
	v_max_f32_e32 v52, v14, v14
	v_max_f32_e32 v51, v52, v51
	v_max_f32_e32 v52, v31, v31
	v_max_f32_e32 v53, v15, v15
	v_max_f32_e32 v52, v53, v52
	v_max3_f32 v2, v2, v51, v52
	v_max_f32_e32 v51, v32, v32
	v_max_f32_e32 v52, v16, v16
	v_max_f32_e32 v51, v52, v51
	v_max_f32_e32 v52, v33, v33
	v_max_f32_e32 v53, v17, v17
	v_max_f32_e32 v52, v53, v52
	v_max3_f32 v2, v2, v51, v52
	v_max_f32_e32 v51, v34, v34
	v_max_f32_e32 v52, v18, v18
	v_max_f32_e32 v51, v52, v51
	v_max_f32_e32 v52, v35, v35
	v_max_f32_e32 v53, v19, v19
	v_max_f32_e32 v52, v53, v52
	v_max3_f32 v2, v2, v51, v52
	v_and_b32_e32 v52, 64, v154
	v_xor_b32_e32 v51, 32, v154
	v_add_u32_e32 v52, 64, v52
	v_cmp_lt_i32_e64 s[6:7], v51, v52
	s_nop 1
	v_cndmask_b32_e64 v51, v154, v51, s[6:7]
	v_lshlrev_b32_e32 v51, 2, v51
	ds_bpermute_b32 v51, v51, v2
	s_waitcnt lgkmcnt(0)
; DI float ex2(float x) { return __builtin_amdgcn_exp2f(x); }
; #define MFMA32(a, b, c) __builtin_amdgcn_mfma_f32_32x32x16_bf16((a), (b), (c), 0, 0, 0)
; DI void pv_step(const char* Vt, const bf16x8 (&pb)[4], f32x16 (&o)[2], int lane) {
;   const int lh = lane >> 5, q4 = (lane & 15) >> 2, p4 = lane & 3, g1 = (lane >> 4) & 1;
;   const char* vb = Vt + (4 * lh + q4) * VS + 32 * g1 + 8 * p4;
; #pragma unroll
;   for (int ks = 0; ks < 4; ++ks) {
; #pragma unroll
;     for (int dvt = 0; dvt < 2; ++dvt) {
;       const s16x4 lo = tr_read(vb + (ks * 16) * VS + dvt * 64);
;       const s16x4 hi = tr_read(vb + (ks * 16 + 8) * VS + dvt * 64);
;       const bf16x8 vf = __builtin_shufflevector(lo, hi, 0, 1, 2, 3, 4, 5, 6, 7);
;       o[dvt] = MFMA32(vf, pb[ks], o[dvt]);
;     }
;   }
; }
; DI void pack_p(const f32x16 (&s)[2], bf16x8 (&pb)[4]) {
; #pragma unroll
;   for (int mt = 0; mt < 2; ++mt)
; #pragma unroll
;     for (int h = 0; h < 2; ++h) {
;       u32x4 t = {pk2(s[mt][8 * h + 0], s[mt][8 * h + 1]), pk2(s[mt][8 * h + 2], s[mt][8 * h + 3]),
;                  pk2(s[mt][8 * h + 4], s[mt][8 * h + 5]), pk2(s[mt][8 * h + 6], s[mt][8 * h + 7])};
;       pb[mt * 2 + h] = __builtin_bit_cast(bf16x8, t);
;     }
; }
; DI void mla_item(const P& p, char* smem, int b, int hd, int q0, bool samp) {
;     ...
;         const float up = (kb == 0) ? mx : fmaxf(mx, 0.f);
;         const float alpha = (kb == 0) ? 0.f : ex2(-up);
;         lsum *= alpha;
; #pragma unroll
;         for (int i = 0; i < 16; ++i) { o[0][i] *= alpha; o[1][i] *= alpha; }
;         mrun = (kb == 0) ? mx : mrun + up;
;         ps0 = 0.f; ps1 = 0.f;
; #pragma unroll
;         for (int i = 0; i < 16; ++i) { e[0][i] = ex2(s[0][i] - up); e[1][i] = ex2(s[1][i] - up); ps0 += e[0][i]; ps1 += e[1][i]; }
;       }
;       lsum += ps0 + ps1;
;       bf16x8 pb[4];
;       pack_p(e, pb);
;       pv_step(Vt, pb, o, lane);
	v_max_f32_e32 v51, v51, v51
	v_max_f32_e32 v161, v2, v51
	v_sub_f32_e32 v4, v4, v161
	v_exp_f32_e32 v64, v4
	v_sub_f32_e32 v4, v5, v161
	v_exp_f32_e32 v66, v4
	v_sub_f32_e32 v4, v6, v161
	v_exp_f32_e32 v96, v4
	v_sub_f32_e32 v4, v7, v161
	v_sub_f32_e32 v2, v20, v161
	v_exp_f32_e32 v98, v4
	v_sub_f32_e32 v4, v8, v161
	v_exp_f32_e32 v65, v2
	v_sub_f32_e32 v2, v21, v161
	v_exp_f32_e32 v100, v4
	v_sub_f32_e32 v4, v9, v161
	v_exp_f32_e32 v67, v2
	v_sub_f32_e32 v2, v22, v161
	v_exp_f32_e32 v102, v4
	v_sub_f32_e32 v4, v10, v161
	v_exp_f32_e32 v97, v2
	v_sub_f32_e32 v2, v23, v161
	v_exp_f32_e32 v108, v4
	v_sub_f32_e32 v4, v11, v161
	v_exp_f32_e32 v99, v2
	v_sub_f32_e32 v2, v24, v161
	v_exp_f32_e32 v110, v4
	v_sub_f32_e32 v4, v12, v161
	v_exp_f32_e32 v101, v2
	v_sub_f32_e32 v2, v25, v161
	v_exp_f32_e32 v112, v4
	v_sub_f32_e32 v4, v13, v161
	v_exp_f32_e32 v103, v2
	v_sub_f32_e32 v2, v26, v161
	v_exp_f32_e32 v114, v4
	v_sub_f32_e32 v4, v14, v161
	v_exp_f32_e32 v109, v2
	v_sub_f32_e32 v2, v27, v161
	v_exp_f32_e32 v116, v4
	v_sub_f32_e32 v4, v15, v161
	v_exp_f32_e32 v111, v2
	v_sub_f32_e32 v2, v28, v161
	v_exp_f32_e32 v118, v4
	v_add_u32_e32 v4, 16, v107
	v_exp_f32_e32 v113, v2
	v_sub_f32_e32 v2, v29, v161
	v_add3_u32 v51, v4, v147, v148
	v_exp_f32_e32 v115, v2
	v_sub_f32_e32 v2, v30, v161
	ds_read_b64_tr_b16 v[4:5], v51 offset:13312
	ds_read_b64_tr_b16 v[6:7], v51 offset:14848
	v_exp_f32_e32 v117, v2
	v_sub_f32_e32 v2, v31, v161
	v_exp_f32_e32 v119, v2
	v_sub_f32_e32 v2, v32, v161
	ds_read_b64_tr_b16 v[14:15], v51 offset:14912
	ds_read_b64_tr_b16 v[12:13], v51 offset:13376
	v_exp_f32_e32 v121, v2
	v_sub_f32_e32 v2, v33, v161
	v_sub_f32_e32 v8, v16, v161
	v_exp_f32_e32 v123, v2
	v_sub_f32_e32 v2, v34, v161
	v_exp_f32_e32 v120, v8
	v_cvt_pk_bf16_f32 v8, v64, v66
	v_cvt_pk_bf16_f32 v9, v96, v98
	v_cvt_pk_bf16_f32 v10, v100, v102
	v_cvt_pk_bf16_f32 v11, v108, v110
	v_exp_f32_e32 v125, v2
	v_sub_f32_e32 v2, v35, v161
	s_waitcnt lgkmcnt(2)
	v_mfma_f32_32x32x16_bf16 v[20:35], v[4:7], v[8:11], 0
	v_sub_f32_e32 v4, v17, v161
	v_exp_f32_e32 v122, v4
	v_sub_f32_e32 v4, v18, v161
	v_exp_f32_e32 v124, v4
	v_sub_f32_e32 v56, v19, v161
	ds_read_b64_tr_b16 v[52:53], v51 offset:16384
	ds_read_b64_tr_b16 v[54:55], v51 offset:17920
	v_exp_f32_e32 v126, v56
	s_waitcnt lgkmcnt(2)
	v_mfma_f32_32x32x16_bf16 v[4:19], v[12:15], v[8:11], 0
	ds_read_b64_tr_b16 v[62:63], v51 offset:17984
	ds_read_b64_tr_b16 v[60:61], v51 offset:16448
	v_cvt_pk_bf16_f32 v56, v112, v114
	v_cvt_pk_bf16_f32 v57, v116, v118
	v_cvt_pk_bf16_f32 v58, v120, v122
	v_cvt_pk_bf16_f32 v59, v124, v126
	v_exp_f32_e32 v127, v2
	s_waitcnt lgkmcnt(2)
	v_mfma_f32_32x32x16_bf16 v[20:35], v[52:55], v[56:59], v[20:35]
	v_add_f32_e64 v52, v64, 0
	v_add_f32_e64 v53, v65, 0
	v_add_f32_e64 v52, v66, v52
	v_add_f32_e64 v53, v67, v53
	v_add_f32_e64 v52, v96, v52
	v_add_f32_e64 v53, v97, v53
	v_add_f32_e32 v128, v98, v52
	v_add_f32_e32 v129, v99, v53
	s_waitcnt lgkmcnt(0)
	v_mfma_f32_32x32x16_bf16 v[4:19], v[60:63], v[56:59], v[4:19]
	ds_read_b64_tr_b16 v[52:53], v51 offset:19456
	ds_read_b64_tr_b16 v[54:55], v51 offset:20992
	ds_read_b64_tr_b16 v[62:63], v51 offset:21056
	ds_read_b64_tr_b16 v[60:61], v51 offset:19520
	v_add_f32_e64 v128, v100, v128
	v_add_f32_e64 v129, v101, v129
	v_cvt_pk_bf16_f32 v56, v65, v67
	v_cvt_pk_bf16_f32 v57, v97, v99
	v_cvt_pk_bf16_f32 v58, v101, v103
	v_cvt_pk_bf16_f32 v59, v109, v111
	s_waitcnt lgkmcnt(2)
	s_nop 0
	v_mfma_f32_32x32x16_bf16 v[20:35], v[52:55], v[56:59], v[20:35]
	v_add_f32_e64 v52, v102, v128
	v_add_f32_e64 v53, v103, v129
	v_add_f32_e64 v52, v108, v52
	v_add_f32_e64 v53, v109, v53
	v_add_f32_e64 v52, v110, v52
	v_add_f32_e64 v53, v111, v53
	v_add_f32_e32 v52, v112, v52
	v_add_f32_e32 v53, v113, v53
	s_waitcnt lgkmcnt(0)
	v_mfma_f32_32x32x16_bf16 v[4:19], v[60:63], v[56:59], v[4:19]
	v_add_f32_e64 v64, v114, v52
	v_add_f32_e64 v65, v115, v53
	ds_read_b64_tr_b16 v[52:53], v51 offset:22528
	ds_read_b64_tr_b16 v[54:55], v51 offset:24064
	ds_read_b64_tr_b16 v[62:63], v51 offset:24128
	ds_read_b64_tr_b16 v[60:61], v51 offset:22592
	v_cvt_pk_bf16_f32 v56, v113, v115
	v_cvt_pk_bf16_f32 v57, v117, v119
	v_cvt_pk_bf16_f32 v58, v121, v123
	v_cvt_pk_bf16_f32 v59, v125, v127
	v_add_f32_e32 v64, v116, v64
	v_add_f32_e32 v65, v117, v65
	s_waitcnt lgkmcnt(2)
	v_mfma_f32_32x32x16_bf16 v[20:35], v[52:55], v[56:59], v[20:35]
	v_add_f32_e64 v52, v118, v64
	v_add_f32_e64 v53, v119, v65
	v_add_f32_e64 v52, v120, v52
	v_add_f32_e64 v53, v121, v53
	v_add_f32_e64 v52, v122, v52
	v_add_f32_e64 v53, v123, v53
	v_add_f32_e32 v52, v124, v52
	v_add_f32_e32 v53, v125, v53
	s_waitcnt lgkmcnt(0)
	v_mfma_f32_32x32x16_bf16 v[4:19], v[60:63], v[56:59], v[4:19]
	v_add_f32_e64 v52, v126, v52
	v_add_f32_e64 v53, v127, v53
	v_add_f32_e32 v2, v52, v53
	v_add_f32_e32 v149, 0, v2
	s_branch .LBB0_405

; DI float ex2(float x) { return __builtin_amdgcn_exp2f(x); }
; #define MFMA32(a, b, c) __builtin_amdgcn_mfma_f32_32x32x16_bf16((a), (b), (c), 0, 0, 0)
; DI void mla_item(const P& p, char* smem, int b, int hd, int q0, bool samp) {
;     ...
;       const char* Kt = smem + (kb & 1) * STG + hoff; const char* Vt = Kt + 64 * KS_MLA;
;       f32x16 s[2];
;       const float cinit = (kb == 0) ? 0.f : -mrun;
; #pragma unroll
;       for (int i = 0; i < 16; ++i) { s[0][i] = cinit; s[1][i] = cinit; }
;       const char* kp = Kt + l32 * KS_MLA + lh * 16;
; #pragma unroll
;       for (int ks = 0; ks < 6; ++ks) {
;         const bf16x8 a0 = *(const bf16x8*)(kp + ks * 32);
;         const bf16x8 a1 = *(const bf16x8*)(kp + 32 * KS_MLA + ks * 32);
;         s[0] = MFMA32(a0, qf[ks], s[0]);
;         s[1] = MFMA32(a1, qf[ks], s[1]);
;       }
;       f32x16 e[2];
;       float ps0 = 0.f, ps1 = 0.f;
;       bool redo = (kb == 0);
;       if (!redo) {
; #pragma unroll
;         for (int i = 0; i < 16; ++i) { e[0][i] = ex2(s[0][i]); e[1][i] = ex2(s[1][i]); ps0 += e[0][i]; ps1 += e[1][i]; }
;         redo = (__builtin_amdgcn_ballot_w64(!(ps0 + ps1 < 1e18f)) != 0ull);
;       }
.LBB0_420:
	s_or_b32 s4, s53, 2
	s_cmp_ge_i32 s4, s60
	s_cbranch_scc1 .LBB0_425
	v_add3_u32 v1, s52, v160, v106
	ds_read_b128 v[92:95], v1
	ds_read_b128 v[96:99], v1 offset:32
	v_xor_b32_e32 v36, 0x80000000, v161
	v_mov_b32_e32 v37, v36
	v_mov_b32_e32 v38, v36
	v_mov_b32_e32 v39, v36
	v_mov_b32_e32 v40, v36
	v_mov_b32_e32 v41, v36
	v_mov_b32_e32 v42, v36
	v_mov_b32_e32 v43, v36
	v_mov_b32_e32 v44, v36
	v_mov_b32_e32 v45, v36
	v_mov_b32_e32 v46, v36
	v_mov_b32_e32 v47, v36
	v_mov_b32_e32 v48, v36
	v_mov_b32_e32 v49, v36
	v_mov_b32_e32 v50, v36
	v_mov_b32_e32 v51, v36
	s_waitcnt lgkmcnt(1)
	s_nop 0
	v_mfma_f32_32x32x16_bf16 v[52:67], v[92:95], v[88:91], v[36:51]
	ds_read_b128 v[92:95], v1 offset:6656
	ds_read_b128 v[100:103], v1 offset:6688
	s_waitcnt lgkmcnt(1)
	v_mfma_f32_32x32x16_bf16 v[36:51], v[92:95], v[88:91], v[36:51]
	v_mfma_f32_32x32x16_bf16 v[52:67], v[96:99], v[84:87], v[52:67]
	s_waitcnt lgkmcnt(0)
	v_mfma_f32_32x32x16_bf16 v[36:51], v[100:103], v[84:87], v[36:51]
	ds_read_b128 v[84:87], v1 offset:64
	ds_read_b128 v[88:91], v1 offset:96
	s_waitcnt lgkmcnt(1)
	v_mfma_f32_32x32x16_bf16 v[52:67], v[84:87], v[80:83], v[52:67]
	ds_read_b128 v[84:87], v1 offset:6720
	ds_read_b128 v[92:95], v1 offset:6752
	s_waitcnt lgkmcnt(1)
	v_mfma_f32_32x32x16_bf16 v[36:51], v[84:87], v[80:83], v[36:51]
	v_mfma_f32_32x32x16_bf16 v[52:67], v[88:91], v[76:79], v[52:67]
	s_waitcnt lgkmcnt(0)
	v_mfma_f32_32x32x16_bf16 v[36:51], v[92:95], v[76:79], v[36:51]
	ds_read_b128 v[76:79], v1 offset:128
	ds_read_b128 v[80:83], v1 offset:160
	s_waitcnt lgkmcnt(1)
	v_mfma_f32_32x32x16_bf16 v[52:67], v[76:79], v[72:75], v[52:67]
	ds_read_b128 v[76:79], v1 offset:6784
	ds_read_b128 v[84:87], v1 offset:6816
	s_waitcnt lgkmcnt(1)
	v_mfma_f32_32x32x16_bf16 v[36:51], v[76:79], v[72:75], v[36:51]
	v_mfma_f32_32x32x16_bf16 v[52:67], v[80:83], v[68:71], v[52:67]
	s_waitcnt lgkmcnt(0)
	v_mfma_f32_32x32x16_bf16 v[36:51], v[84:87], v[68:71], v[36:51]
	s_nop 9
	v_exp_f32_e32 v72, v52
	v_exp_f32_e32 v68, v53
	v_exp_f32_e32 v70, v54
	v_exp_f32_e32 v74, v55
	v_exp_f32_e32 v76, v56
	v_exp_f32_e32 v78, v57
	v_exp_f32_e32 v94, v58
	v_exp_f32_e32 v73, v36
	v_exp_f32_e32 v69, v37
	v_exp_f32_e32 v71, v38
	v_exp_f32_e32 v75, v39
	v_exp_f32_e32 v77, v40
	v_add_f32_e32 v80, 0, v72
	v_add_f32_e32 v81, 0, v73
	v_exp_f32_e32 v79, v41
	v_add_f32_e32 v80, v68, v80
	v_add_f32_e32 v81, v69, v81
	v_exp_f32_e32 v95, v42
	v_add_f32_e32 v80, v70, v80
	v_add_f32_e32 v81, v71, v81
	v_exp_f32_e32 v96, v59
	v_add_f32_e32 v80, v74, v80
	v_add_f32_e32 v81, v75, v81
	v_exp_f32_e32 v97, v43
	v_add_f32_e32 v80, v76, v80
	v_add_f32_e32 v81, v77, v81
	v_exp_f32_e32 v82, v61
	v_add_f32_e32 v98, v78, v80
	v_add_f32_e32 v99, v79, v81
	v_exp_f32_e32 v80, v60
	v_exp_f32_e32 v81, v44
	v_exp_f32_e32 v83, v45
	v_exp_f32_e32 v84, v62
	v_exp_f32_e32 v85, v46
	v_add_f32_e32 v98, v94, v98
	v_add_f32_e32 v99, v95, v99
	v_exp_f32_e32 v86, v63
	v_exp_f32_e32 v87, v47
	v_add_f32_e32 v98, v96, v98
	v_add_f32_e32 v99, v97, v99
	v_exp_f32_e32 v88, v64
	v_exp_f32_e32 v89, v48
	v_add_f32_e32 v98, v80, v98
	v_add_f32_e32 v99, v81, v99
	v_exp_f32_e32 v90, v65
	v_exp_f32_e32 v91, v49
	v_add_f32_e32 v98, v82, v98
	v_add_f32_e32 v99, v83, v99
	v_exp_f32_e32 v92, v66
	v_exp_f32_e32 v93, v50
	v_add_f32_e32 v98, v84, v98
	v_add_f32_e32 v99, v85, v99
	v_exp_f32_e32 v100, v67
	v_exp_f32_e32 v101, v51
	v_add_f32_e32 v98, v86, v98
	v_add_f32_e32 v99, v87, v99
	s_nop 0
	v_add_f32_e32 v98, v88, v98
	v_add_f32_e32 v99, v89, v99
	s_nop 0
	v_add_f32_e32 v98, v90, v98
	v_add_f32_e32 v99, v91, v99
	s_nop 0
	v_add_f32_e32 v98, v92, v98
	v_add_f32_e32 v99, v93, v99
	s_nop 0
	v_add_f32_e32 v98, v100, v98
	v_add_f32_e32 v99, v101, v99
	s_nop 0
	v_add_f32_e32 v1, v98, v99
	v_cmp_ngt_f32_e32 vcc, s79, v1
	s_cbranch_vccz .LBB0_423
; DI float ex2(float x) { return __builtin_amdgcn_exp2f(x); }
; DI void mla_item(const P& p, char* smem, int b, int hd, int q0, bool samp) {
;     ...
;       if (redo) {
;         float mx = fmaxf(s[0][0], s[1][0]);
; #pragma unroll
;         for (int i = 1; i < 16; ++i) mx = fmaxf(mx, fmaxf(s[0][i], s[1][i]));
;         mx = fmaxf(mx, __shfl_xor(mx, 32));
;         const float up = (kb == 0) ? mx : fmaxf(mx, 0.f);
;         const float alpha = (kb == 0) ? 0.f : ex2(-up);
;         lsum *= alpha;
; #pragma unroll
;         for (int i = 0; i < 16; ++i) { o[0][i] *= alpha; o[1][i] *= alpha; }
;         mrun = (kb == 0) ? mx : mrun + up;
;         ps0 = 0.f; ps1 = 0.f;
; #pragma unroll
;         for (int i = 0; i < 16; ++i) { e[0][i] = ex2(s[0][i] - up); e[1][i] = ex2(s[1][i] - up); ps0 += e[0][i]; ps1 += e[1][i]; }
;       }
;       lsum += ps0 + ps1;
	v_max_f32_e32 v1, v37, v37
	v_max_f32_e32 v2, v53, v53
	v_max_f32_e32 v1, v2, v1
	v_max_f32_e32 v2, v38, v38
	v_max_f32_e32 v68, v54, v54
	v_max_f32_e32 v2, v68, v2
	v_max_f32_e32 v68, v39, v39
	v_max_f32_e32 v69, v55, v55
	v_max3_f32 v1, v52, v36, v1
	v_max_f32_e32 v68, v69, v68
	v_max3_f32 v1, v1, v2, v68
	v_max_f32_e32 v2, v40, v40
	v_max_f32_e32 v68, v56, v56
	v_max_f32_e32 v2, v68, v2
	v_max_f32_e32 v68, v41, v41
	v_max_f32_e32 v69, v57, v57
	v_max_f32_e32 v68, v69, v68
	v_max3_f32 v1, v1, v2, v68
	v_max_f32_e32 v2, v42, v42
	v_max_f32_e32 v68, v58, v58
	v_max_f32_e32 v2, v68, v2
	v_max_f32_e32 v68, v43, v43
	v_max_f32_e32 v69, v59, v59
	v_max_f32_e32 v68, v69, v68
	v_max3_f32 v1, v1, v2, v68
	v_max_f32_e32 v2, v44, v44
	v_max_f32_e32 v68, v60, v60
	v_max_f32_e32 v2, v68, v2
	v_max_f32_e32 v68, v45, v45
	v_max_f32_e32 v69, v61, v61
	v_max_f32_e32 v68, v69, v68
	v_max3_f32 v1, v1, v2, v68
	v_max_f32_e32 v2, v46, v46
	v_max_f32_e32 v68, v62, v62
	v_max_f32_e32 v2, v68, v2
	v_max_f32_e32 v68, v47, v47
	v_max_f32_e32 v69, v63, v63
	v_max_f32_e32 v68, v69, v68
	v_max3_f32 v1, v1, v2, v68
	v_max_f32_e32 v2, v48, v48
	v_max_f32_e32 v68, v64, v64
	v_max_f32_e32 v2, v68, v2
	v_max_f32_e32 v68, v49, v49
	v_max_f32_e32 v69, v65, v65
	v_max_f32_e32 v68, v69, v68
	v_max3_f32 v1, v1, v2, v68
	v_max_f32_e32 v2, v50, v50
	v_max_f32_e32 v68, v66, v66
	v_max_f32_e32 v2, v68, v2
	v_max_f32_e32 v68, v51, v51
	v_max_f32_e32 v69, v67, v67
	v_max_f32_e32 v68, v69, v68
	v_max3_f32 v1, v1, v2, v68
	v_and_b32_e32 v68, 64, v154
	v_xor_b32_e32 v2, 32, v154
	v_add_u32_e32 v68, 64, v68
	v_cmp_lt_i32_e32 vcc, v2, v68
	s_nop 1
	v_cndmask_b32_e32 v2, v154, v2, vcc
	v_lshlrev_b32_e32 v2, 2, v2
	ds_bpermute_b32 v2, v2, v1
	s_waitcnt lgkmcnt(0)
	v_max3_f32 v1, v1, v2, 0
	v_sub_f32_e32 v2, v52, v1
	v_exp_f32_e32 v72, v2
	v_sub_f32_e32 v2, v36, v1
	v_exp_f32_e32 v73, v2
	v_sub_f32_e32 v2, v53, v1
	v_exp_f32_e32 v68, v2
	v_sub_f32_e32 v2, v37, v1
	v_exp_f32_e32 v69, v2
	v_sub_f32_e32 v2, v54, v1
	v_exp_f32_e32 v70, v2
	v_sub_f32_e32 v2, v38, v1
	v_exp_f32_e32 v71, v2
	v_sub_f32_e32 v2, v55, v1
	v_exp_f32_e32 v74, v2
	v_sub_f32_e32 v2, v39, v1
	v_exp_f32_e32 v75, v2
	v_sub_f32_e32 v2, v56, v1
	v_exp_f32_e32 v76, v2
	v_sub_f32_e32 v2, v40, v1
	v_exp_f32_e32 v77, v2
	v_sub_f32_e32 v2, v57, v1
	v_exp_f32_e32 v78, v2
	v_sub_f32_e32 v2, v41, v1
	v_exp_f32_e32 v79, v2
	v_sub_f32_e32 v2, v58, v1
	v_exp_f32_e32 v94, v2
	v_sub_f32_e32 v2, v42, v1
	v_exp_f32_e32 v95, v2
	v_sub_f32_e32 v2, v59, v1
	v_exp_f32_e32 v96, v2
	v_sub_f32_e32 v2, v43, v1
	v_exp_f32_e32 v97, v2
	v_sub_f32_e32 v2, v60, v1
	v_exp_f32_e32 v80, v2
	v_sub_f32_e32 v2, v44, v1
	v_exp_f32_e32 v81, v2
	v_sub_f32_e32 v2, v61, v1
	v_exp_f32_e32 v82, v2
	v_sub_f32_e32 v2, v45, v1
	v_add_f32_e32 v36, 0, v72
	v_add_f32_e32 v37, 0, v73
	v_exp_f32_e32 v83, v2
	v_sub_f32_e32 v2, v62, v1
	v_add_f32_e32 v36, v68, v36
	v_add_f32_e32 v37, v69, v37
	v_exp_f32_e32 v84, v2
	v_sub_f32_e32 v2, v46, v1
	v_add_f32_e32 v36, v70, v36
	v_add_f32_e32 v37, v71, v37
	v_exp_f32_e32 v85, v2
	v_sub_f32_e32 v2, v63, v1
	v_add_f32_e32 v36, v74, v36
	v_add_f32_e32 v37, v75, v37
	v_exp_f32_e32 v86, v2
	v_sub_f32_e32 v2, v47, v1
	v_add_f32_e32 v36, v76, v36
	v_add_f32_e32 v37, v77, v37
	v_exp_f32_e32 v87, v2
	v_sub_f32_e32 v2, v64, v1
	v_add_f32_e32 v36, v78, v36
	v_add_f32_e32 v37, v79, v37
	v_exp_f32_e32 v88, v2
	v_sub_f32_e32 v2, v48, v1
	v_exp_f32_e32 v89, v2
	v_sub_f32_e32 v2, v65, v1
	v_add_f32_e32 v36, v94, v36
	v_add_f32_e32 v37, v95, v37
	v_exp_f32_e32 v90, v2
	v_sub_f32_e32 v2, v49, v1
	v_add_f32_e32 v36, v96, v36
	v_add_f32_e32 v37, v97, v37
	v_exp_f32_e32 v91, v2
	v_sub_f32_e32 v2, v66, v1
	v_add_f32_e32 v36, v80, v36
	v_add_f32_e32 v37, v81, v37
	v_exp_f32_e32 v92, v2
	v_sub_f32_e32 v2, v50, v1
	v_add_f32_e32 v36, v82, v36
	v_add_f32_e32 v37, v83, v37
	v_exp_f32_e32 v93, v2
	v_add_f32_e32 v36, v84, v36
	v_add_f32_e32 v37, v85, v37
	v_exp_f32_e64 v102, -v1
	v_add_f32_e32 v36, v86, v36
	v_add_f32_e32 v37, v87, v37
	v_sub_f32_e32 v2, v67, v1
	v_add_f32_e32 v36, v88, v36
	v_add_f32_e32 v37, v89, v37
	v_sub_f32_e32 v1, v51, v1
	v_add_f32_e32 v36, v90, v36
	v_add_f32_e32 v37, v91, v37
	v_exp_f32_e32 v100, v2
	v_add_f32_e32 v46, v92, v36
	v_add_f32_e32 v47, v93, v37
	v_exp_f32_e32 v37, v1
	v_pk_mul_f32 v[18:19], v[18:19], v[102:103] op_sel_hi:[1,0]
	v_pk_mul_f32 v[16:17], v[16:17], v[102:103] op_sel_hi:[1,0]
	v_pk_mul_f32 v[14:15], v[14:15], v[102:103] op_sel_hi:[1,0]
	v_mov_b32_e32 v101, v37
	v_pk_mul_f32 v[12:13], v[12:13], v[102:103] op_sel_hi:[1,0]
	v_pk_mul_f32 v[10:11], v[10:11], v[102:103] op_sel_hi:[1,0]
	v_pk_mul_f32 v[8:9], v[8:9], v[102:103] op_sel_hi:[1,0]
	v_pk_mul_f32 v[6:7], v[6:7], v[102:103] op_sel_hi:[1,0]
	v_pk_mul_f32 v[4:5], v[4:5], v[102:103] op_sel_hi:[1,0]
	v_mov_b32_e32 v2, v73
	v_mov_b32_e32 v1, v69
	v_mov_b32_e32 v42, v71
	v_mov_b32_e32 v45, v75
	v_mov_b32_e32 v38, v77
	v_mov_b32_e32 v41, v79
	v_mov_b32_e32 v40, v95
	v_mov_b32_e32 v43, v97
	v_mov_b32_e32 v36, v81
	v_mov_b32_e32 v39, v83
	v_add_f32_e32 v98, v100, v46
	v_add_f32_e32 v99, v101, v47
	v_pk_mul_f32 v[34:35], v[34:35], v[102:103] op_sel_hi:[1,0]
	v_pk_mul_f32 v[32:33], v[32:33], v[102:103] op_sel_hi:[1,0]
	v_pk_mul_f32 v[30:31], v[30:31], v[102:103] op_sel_hi:[1,0]
	v_pk_mul_f32 v[28:29], v[28:29], v[102:103] op_sel_hi:[1,0]
	v_pk_mul_f32 v[26:27], v[26:27], v[102:103] op_sel_hi:[1,0]
	v_pk_mul_f32 v[24:25], v[24:25], v[102:103] op_sel_hi:[1,0]
	v_pk_mul_f32 v[22:23], v[22:23], v[102:103] op_sel_hi:[1,0]
	v_pk_mul_f32 v[20:21], v[20:21], v[102:103] op_sel_hi:[1,0]
	v_mul_f32_e32 v149, v149, v102
	v_mov_b32_e32 v44, v85
	v_mov_b32_e32 v47, v87
	v_mov_b32_e32 v46, v89
	v_mov_b32_e32 v49, v91
	v_mov_b32_e32 v48, v93
	s_branch .LBB0_424

; DI void mla_item(const P& p, char* smem, int b, int hd, int q0, bool samp) {
;     ...
;   auto gload = [&](int kb) {
;     const size_t trow0 = samp ? (kb < 64 ? (size_t)(NTOK + b * PAST + kb * 64) : (size_t)(NTOK_P + b * 64)) : (size_t)(b * 2048 + kb * 64);
;     if (samp) {
;       const int h2 = tid >> 8, u = tid & 255;
;       const u16* base = kv + (trow0 + (u >> 3)) * 1024 + (hd + h2) * 128 + (u & 7) * 8;
;       rkn = *(const u32x4*)base; rvv = *(const u32x4*)(base + 64);
;       rkn2 = *(const u32x4*)(base + 32 * 1024); rvv2 = *(const u32x4*)(base + 32 * 1024 + 64);
;       rkr = *(const u32x4*)(krope + (trow0 + (u >> 2)) * 32 + (u & 3) * 8);
;     } else {
;       const size_t row = trow0 + (tid >> 3);
;       const u16* base = kv + row * 1024 + hd * 128 + (tid & 7) * 8;
;       rkn = *(const u32x4*)base;
;       rvv = *(const u32x4*)(base + 64);
;       if (tid < 256) rkr = *(const u32x4*)(krope + (trow0 + (tid >> 2)) * 32 + (tid & 3) * 8);
;     }
;   };
;   auto lstore = [&](int buf) {
;     if (samp) {
;       const int h2 = tid >> 8, u = tid & 255;
;       char* Kt = smem + buf * STG + h2 * MLA_STAGE; char* Vt = Kt + 64 * KS_MLA;
;       *(u32x4*)(Kt + (u >> 3) * KS_MLA + (u & 7) * 16) = rkn;
;       *(u32x4*)(Kt + (32 + (u >> 3)) * KS_MLA + (u & 7) * 16) = rkn2;
;       *(u32x4*)(Vt + (u >> 3) * VS + (u & 7) * 16) = rvv;
;       *(u32x4*)(Vt + (32 + (u >> 3)) * VS + (u & 7) * 16) = rvv2;
;       *(u32x4*)(Kt + (u >> 2) * KS_MLA + 128 + (u & 3) * 16) = rkr;
;     } else {
;       char* Kt = smem + buf * STG; char* Vt = Kt + 64 * KS_MLA;
;       *(u32x4*)(Kt + (tid >> 3) * KS_MLA + (tid & 7) * 16) = rkn;
;       *(u32x4*)(Vt + (tid >> 3) * VS + (tid & 7) * 16) = rvv;
;       if (tid < 256) *(u32x4*)(Kt + (tid >> 2) * KS_MLA + 128 + (tid & 3) * 16) = rkr;
;     }
;   };
;   f32x16 o[2];
; #pragma unroll
;   for (int i = 0; i < 16; ++i) { o[0][i] = 0.f; o[1][i] = 0.f; }
;   float mrun = -1e30f, lsum = 0.f;
;   gload(0); lstore(0);
;   __syncthreads();
;     ...
;       f32x16 s[2];
;       const float cinit = (kb == 0) ? 0.f : -mrun;
; #pragma unroll
;       for (int i = 0; i < 16; ++i) { s[0][i] = cinit; s[1][i] = cinit; }
;       const char* kp = Kt + l32 * KS_MLA + lh * 16;
; #pragma unroll
;       for (int ks = 0; ks < 6; ++ks) {
;         const bf16x8 a0 = *(const bf16x8*)(kp + ks * 32);
.LBB0_451:
	s_lshl_b32 s63, s62, 12
	s_add_i32 s62, s63, 0x10400
	s_ashr_i32 s64, s62, 31
	v_ashrrev_i32_e32 v5, 8, v1
	v_bfe_u32 v113, v1, 3, 5
	v_or_b32_e32 v22, s62, v113
	v_mov_b32_e32 v23, s64
	v_add_lshl_u32 v8, v5, s5, 7
	v_lshlrev_b64 v[6:7], 11, v[22:23]
	v_ashrrev_i32_e32 v9, 31, v8
	v_lshl_add_u64 v[6:7], s[26:27], 0, v[6:7]
	v_lshlrev_b64 v[26:27], 1, v[8:9]
	v_lshlrev_b32_e32 v28, 4, v1
	v_lshl_add_u64 v[6:7], v[6:7], 0, v[26:27]
	v_and_b32_e32 v2, 0x70, v28
	v_lshl_add_u64 v[14:15], v[6:7], 0, v[2:3]
	v_add_co_u32_e32 v18, vcc, s80, v14
	v_bfe_u32 v169, v1, 2, 6
	s_nop 0
	v_addc_co_u32_e32 v19, vcc, 0, v15, vcc
	v_lshlrev_b32_e32 v24, 3, v1
	global_load_dwordx4 v[6:9], v[14:15], off
	global_load_dwordx4 v[10:13], v[14:15], off offset:128
	s_nop 0
	global_load_dwordx4 v[14:17], v[18:19], off
	s_nop 0
	global_load_dwordx4 v[18:21], v[18:19], off offset:128
	v_or_b32_e32 v22, s62, v169
	v_lshlrev_b64 v[22:23], 6, v[22:23]
	v_and_b32_e32 v24, 24, v24
	v_lshl_add_u64 v[22:23], s[34:35], 0, v[22:23]
	s_waitcnt vmcnt(4)
	v_lshlrev_b32_e32 v96, 1, v24
	v_mov_b32_e32 v97, v3
	v_lshl_add_u64 v[22:23], v[22:23], 0, v[96:97]
	global_load_dwordx4 v[22:25], v[22:23], off
	v_mad_i32_i24 v170, v5, s83, 16
	v_mad_u32_u24 v171, v113, s78, v155
	s_add_i32 s5, s63, 0x10440
	v_mad_u32_u24 v172, v113, s72, v156
	v_add_u32_e32 v29, v170, v171
	s_ashr_i32 s62, s5, 31
	v_and_b32_e32 v173, 48, v28
	v_mad_u32_u24 v30, v113, s72, v170
	v_add_u32_e32 v31, v170, v172
	v_or_b32_e32 v28, s5, v113
	v_add_u32_e32 v164, v29, v2
	v_mov_b32_e32 v29, s62
	v_lshl_add_u64 v[26:27], s[26:27], 0, v[26:27]
	v_add_u32_e32 v165, v30, v2
	v_add_u32_e32 v166, v31, v2
	v_lshlrev_b64 v[30:31], 11, v[28:29]
	v_or_b32_e32 v28, s5, v169
	v_lshl_add_u64 v[114:115], v[26:27], 0, v[2:3]
	v_mad_u32_u24 v5, v113, s78, v170
	v_lshlrev_b64 v[26:27], 6, v[28:29]
	v_lshl_add_u64 v[28:29], v[114:115], 0, v[30:31]
	v_mad_u32_u24 v32, v169, s78, v170
	v_add_u32_e32 v163, v5, v2
	v_lshl_add_u64 v[26:27], s[34:35], 0, v[26:27]
	v_add_co_u32_e32 v30, vcc, 0x10000, v28
	v_add_u32_e32 v167, v32, v173
	v_lshl_add_u64 v[26:27], v[26:27], 0, v[96:97]
	v_addc_co_u32_e32 v31, vcc, 0, v29, vcc
	v_and_b32_e32 v5, 63, v1
	v_mul_u32_u24_e32 v174, 0xd0, v4
	v_bfe_u32 v4, v1, 2, 2
	v_lshrrev_b32_e32 v1, 3, v1
	v_and_or_b32 v1, v1, 4, v4
	v_mul_u32_u24_e32 v175, 0xc0, v1
	v_lshlrev_b32_e32 v1, 1, v5
	s_mulk_i32 s4, 0x6400
	v_and_b32_e32 v176, 32, v1
	v_lshlrev_b32_e32 v1, 3, v5
	s_add_i32 s62, s4, 16
	v_and_b32_e32 v177, 24, v1
	v_cndmask_b32_e64 v1, 0, 1, s[6:7]
	v_cmp_ne_u32_e64 s[4:5], 1, v1
	v_add_u32_e32 v1, s62, v175
	s_andn2_b64 vcc, exec, s[6:7]
	v_add3_u32 v162, s62, v174, v112
	v_add3_u32 v160, v1, v176, v177
	s_waitcnt vmcnt(4)
	ds_write_b128 v163, v[6:9]
	s_waitcnt vmcnt(2)
	ds_write_b128 v164, v[14:17]
	ds_write_b128 v165, v[10:13] offset:13312
	s_waitcnt vmcnt(1)
	ds_write_b128 v166, v[18:21] offset:13312
	s_waitcnt vmcnt(0)
	ds_write_b128 v167, v[22:25] offset:128
	s_waitcnt lgkmcnt(0)
	s_barrier
	global_load_dwordx4 v[56:59], v[28:29], off
	global_load_dwordx4 v[52:55], v[28:29], off offset:128
	global_load_dwordx4 v[92:95], v[30:31], off
	global_load_dwordx4 v[60:63], v[30:31], off offset:128
	global_load_dwordx4 v[64:67], v[26:27], off
	s_cbranch_vccnz .LBB0_453
	ds_read_b128 v[4:7], v162
	ds_read_b128 v[36:39], v162 offset:32
	ds_read_b128 v[20:23], v162 offset:6656
	ds_read_b128 v[40:43], v162 offset:6688
	s_waitcnt lgkmcnt(3)
	v_mfma_f32_32x32x16_bf16 v[4:19], v[4:7], v[88:91], 0
	s_waitcnt lgkmcnt(1)
	v_mfma_f32_32x32x16_bf16 v[20:35], v[20:23], v[88:91], 0
	v_mfma_f32_32x32x16_bf16 v[4:19], v[36:39], v[84:87], v[4:19]
	s_waitcnt lgkmcnt(0)
	v_mfma_f32_32x32x16_bf16 v[20:35], v[40:43], v[84:87], v[20:35]
	ds_read_b128 v[36:39], v162 offset:64
	ds_read_b128 v[40:43], v162 offset:96
	s_waitcnt lgkmcnt(1)
	v_mfma_f32_32x32x16_bf16 v[4:19], v[36:39], v[80:83], v[4:19]
	ds_read_b128 v[36:39], v162 offset:6720
	ds_read_b128 v[44:47], v162 offset:6752
	s_waitcnt lgkmcnt(1)
	v_mfma_f32_32x32x16_bf16 v[20:35], v[36:39], v[80:83], v[20:35]
	v_mfma_f32_32x32x16_bf16 v[4:19], v[40:43], v[76:79], v[4:19]
	ds_read_b128 v[36:39], v162 offset:128
	ds_read_b128 v[40:43], v162 offset:160
	s_waitcnt lgkmcnt(2)
	v_mfma_f32_32x32x16_bf16 v[20:35], v[44:47], v[76:79], v[20:35]
	s_waitcnt lgkmcnt(1)
	v_mfma_f32_32x32x16_bf16 v[4:19], v[36:39], v[72:75], v[4:19]
	ds_read_b128 v[36:39], v162 offset:6784
	ds_read_b128 v[44:47], v162 offset:6816
	s_waitcnt lgkmcnt(1)
	v_mfma_f32_32x32x16_bf16 v[20:35], v[36:39], v[72:75], v[20:35]
	s_waitcnt lgkmcnt(0)
	v_mfma_f32_32x32x16_bf16 v[20:35], v[44:47], v[68:71], v[20:35]
	v_mfma_f32_32x32x16_bf16 v[4:19], v[40:43], v[68:71], v[4:19]
	s_nop 10
	v_max_f32_e32 v1, v21, v21
	v_max_f32_e32 v36, v5, v5
	v_max_f32_e32 v1, v36, v1
	v_max_f32_e32 v36, v22, v22
	v_max_f32_e32 v37, v6, v6
	v_max_f32_e32 v36, v37, v36
	v_max_f32_e32 v37, v23, v23
	v_max_f32_e32 v38, v7, v7
	v_max3_f32 v1, v4, v20, v1
	v_max_f32_e32 v37, v38, v37
	v_max3_f32 v1, v1, v36, v37
	v_max_f32_e32 v36, v24, v24
	v_max_f32_e32 v37, v8, v8
	v_max_f32_e32 v36, v37, v36
	v_max_f32_e32 v37, v25, v25
	v_max_f32_e32 v38, v9, v9
	v_max_f32_e32 v37, v38, v37
	v_max3_f32 v1, v1, v36, v37
	v_max_f32_e32 v36, v26, v26
	v_max_f32_e32 v37, v10, v10
	v_max_f32_e32 v36, v37, v36
	v_max_f32_e32 v37, v27, v27
	v_max_f32_e32 v38, v11, v11
	v_max_f32_e32 v37, v38, v37
	v_max3_f32 v1, v1, v36, v37
	v_max_f32_e32 v36, v28, v28
	v_max_f32_e32 v37, v12, v12
	v_max_f32_e32 v36, v37, v36
	v_max_f32_e32 v37, v29, v29
	v_max_f32_e32 v38, v13, v13
	v_max_f32_e32 v37, v38, v37
	v_max3_f32 v1, v1, v36, v37
	v_max_f32_e32 v36, v30, v30
	v_max_f32_e32 v37, v14, v14
	v_max_f32_e32 v36, v37, v36
	v_max_f32_e32 v37, v31, v31
	v_max_f32_e32 v38, v15, v15
	v_max_f32_e32 v37, v38, v37
	v_max3_f32 v1, v1, v36, v37
	v_max_f32_e32 v36, v32, v32
	v_max_f32_e32 v37, v16, v16
	v_max_f32_e32 v36, v37, v36
	v_max_f32_e32 v37, v33, v33
	v_max_f32_e32 v38, v17, v17
	v_max_f32_e32 v37, v38, v37
	v_max3_f32 v1, v1, v36, v37
	v_max_f32_e32 v36, v34, v34
	v_max_f32_e32 v37, v18, v18
	v_max_f32_e32 v36, v37, v36
	v_max_f32_e32 v37, v35, v35
	v_max_f32_e32 v38, v19, v19
	v_max_f32_e32 v37, v38, v37
	v_max3_f32 v1, v1, v36, v37
	v_and_b32_e32 v37, 64, v154
	v_xor_b32_e32 v36, 32, v154
	v_add_u32_e32 v37, 64, v37
	v_cmp_lt_i32_e32 vcc, v36, v37
	s_nop 1
	v_cndmask_b32_e32 v36, v154, v36, vcc
	v_lshlrev_b32_e32 v36, 2, v36
	ds_bpermute_b32 v36, v36, v1
	s_waitcnt lgkmcnt(0)
; DI float ex2(float x) { return __builtin_amdgcn_exp2f(x); }
; #define MFMA32(a, b, c) __builtin_amdgcn_mfma_f32_32x32x16_bf16((a), (b), (c), 0, 0, 0)
; DI void pv_step(const char* Vt, const bf16x8 (&pb)[4], f32x16 (&o)[2], int lane) {
;   const int lh = lane >> 5, q4 = (lane & 15) >> 2, p4 = lane & 3, g1 = (lane >> 4) & 1;
;   const char* vb = Vt + (4 * lh + q4) * VS + 32 * g1 + 8 * p4;
; #pragma unroll
;   for (int ks = 0; ks < 4; ++ks) {
; #pragma unroll
;     for (int dvt = 0; dvt < 2; ++dvt) {
;       const s16x4 lo = tr_read(vb + (ks * 16) * VS + dvt * 64);
;       const s16x4 hi = tr_read(vb + (ks * 16 + 8) * VS + dvt * 64);
;       const bf16x8 vf = __builtin_shufflevector(lo, hi, 0, 1, 2, 3, 4, 5, 6, 7);
;       o[dvt] = MFMA32(vf, pb[ks], o[dvt]);
;     }
;   }
; }
; DI void pack_p(const f32x16 (&s)[2], bf16x8 (&pb)[4]) {
; #pragma unroll
;   for (int mt = 0; mt < 2; ++mt)
; #pragma unroll
;     for (int h = 0; h < 2; ++h) {
;       u32x4 t = {pk2(s[mt][8 * h + 0], s[mt][8 * h + 1]), pk2(s[mt][8 * h + 2], s[mt][8 * h + 3]),
;                  pk2(s[mt][8 * h + 4], s[mt][8 * h + 5]), pk2(s[mt][8 * h + 6], s[mt][8 * h + 7])};
;       pb[mt * 2 + h] = __builtin_bit_cast(bf16x8, t);
;     }
; }
; DI void mla_item(const P& p, char* smem, int b, int hd, int q0, bool samp) {
;     ...
;         const float up = (kb == 0) ? mx : fmaxf(mx, 0.f);
;         const float alpha = (kb == 0) ? 0.f : ex2(-up);
;         lsum *= alpha;
; #pragma unroll
;         for (int i = 0; i < 16; ++i) { o[0][i] *= alpha; o[1][i] *= alpha; }
;         mrun = (kb == 0) ? mx : mrun + up;
;         ps0 = 0.f; ps1 = 0.f;
; #pragma unroll
;         for (int i = 0; i < 16; ++i) { e[0][i] = ex2(s[0][i] - up); e[1][i] = ex2(s[1][i] - up); ps0 += e[0][i]; ps1 += e[1][i]; }
;       }
;       lsum += ps0 + ps1;
;       bf16x8 pb[4];
;       pack_p(e, pb);
;       pv_step(Vt, pb, o, lane);
	v_max_f32_e32 v36, v36, v36
	v_max_f32_e32 v168, v1, v36
	v_sub_f32_e32 v4, v4, v168
	v_exp_f32_e32 v98, v4
	v_sub_f32_e32 v4, v5, v168
	v_exp_f32_e32 v100, v4
	v_sub_f32_e32 v4, v6, v168
	v_sub_f32_e32 v1, v20, v168
	v_exp_f32_e32 v102, v4
	v_sub_f32_e32 v4, v7, v168
	v_exp_f32_e32 v99, v1
	v_sub_f32_e32 v1, v21, v168
	v_exp_f32_e32 v104, v4
	v_sub_f32_e32 v4, v8, v168
	v_exp_f32_e32 v101, v1
	v_sub_f32_e32 v1, v22, v168
	v_exp_f32_e32 v106, v4
	v_sub_f32_e32 v4, v9, v168
	v_exp_f32_e32 v103, v1
	v_sub_f32_e32 v1, v23, v168
	v_exp_f32_e32 v108, v4
	v_sub_f32_e32 v4, v10, v168
	v_exp_f32_e32 v105, v1
	v_sub_f32_e32 v1, v24, v168
	v_exp_f32_e32 v110, v4
	v_sub_f32_e32 v4, v11, v168
	v_exp_f32_e32 v107, v1
	v_sub_f32_e32 v1, v25, v168
	v_exp_f32_e32 v116, v4
	v_sub_f32_e32 v4, v12, v168
	v_exp_f32_e32 v109, v1
	v_sub_f32_e32 v1, v26, v168
	v_exp_f32_e32 v118, v4
	v_sub_f32_e32 v4, v13, v168
	v_exp_f32_e32 v111, v1
	v_sub_f32_e32 v1, v27, v168
	v_exp_f32_e32 v120, v4
	v_sub_f32_e32 v4, v14, v168
	v_exp_f32_e32 v117, v1
	v_sub_f32_e32 v1, v28, v168
	v_exp_f32_e32 v122, v4
	v_sub_f32_e32 v4, v15, v168
	v_exp_f32_e32 v119, v1
	v_sub_f32_e32 v1, v29, v168
	v_exp_f32_e32 v124, v4
	ds_read_b64_tr_b16 v[4:5], v160 offset:13312
	ds_read_b64_tr_b16 v[6:7], v160 offset:14848
	v_exp_f32_e32 v121, v1
	v_sub_f32_e32 v1, v30, v168
	ds_read_b64_tr_b16 v[14:15], v160 offset:14912
	ds_read_b64_tr_b16 v[12:13], v160 offset:13376
	v_exp_f32_e32 v123, v1
	v_sub_f32_e32 v1, v31, v168
	v_exp_f32_e32 v125, v1
	v_sub_f32_e32 v1, v32, v168
	v_sub_f32_e32 v8, v16, v168
	v_exp_f32_e32 v127, v1
	v_sub_f32_e32 v1, v33, v168
	v_exp_f32_e32 v126, v8
	v_cvt_pk_bf16_f32 v8, v98, v100
	v_cvt_pk_bf16_f32 v9, v102, v104
	v_cvt_pk_bf16_f32 v10, v106, v108
	v_cvt_pk_bf16_f32 v11, v110, v116
	v_exp_f32_e32 v129, v1
	v_sub_f32_e32 v1, v34, v168
	s_waitcnt lgkmcnt(2)
	v_mfma_f32_32x32x16_bf16 v[36:51], v[4:7], v[8:11], 0
	v_exp_f32_e32 v131, v1
	v_sub_f32_e32 v1, v35, v168
	v_sub_f32_e32 v4, v17, v168
	v_exp_f32_e32 v128, v4
	v_sub_f32_e32 v4, v18, v168
	v_sub_f32_e32 v16, v19, v168
	v_exp_f32_e32 v130, v4
	s_waitcnt lgkmcnt(0)
	v_mfma_f32_32x32x16_bf16 v[20:35], v[12:15], v[8:11], 0
	ds_read_b64_tr_b16 v[4:5], v160 offset:16384
	ds_read_b64_tr_b16 v[6:7], v160 offset:17920
	v_exp_f32_e32 v16, v16
	ds_read_b64_tr_b16 v[14:15], v160 offset:17984
	ds_read_b64_tr_b16 v[12:13], v160 offset:16448
	v_cvt_pk_bf16_f32 v8, v118, v120
	v_cvt_pk_bf16_f32 v9, v122, v124
	v_cvt_pk_bf16_f32 v10, v126, v128
	v_cvt_pk_bf16_f32 v11, v130, v16
	v_exp_f32_e32 v17, v1
	s_waitcnt lgkmcnt(2)
	v_mfma_f32_32x32x16_bf16 v[36:51], v[4:7], v[8:11], v[36:51]
	v_add_f32_e64 v4, v98, 0
	v_add_f32_e64 v5, v99, 0
	v_add_f32_e64 v4, v100, v4
	v_add_f32_e64 v5, v101, v5
	v_add_f32_e64 v4, v102, v4
	v_add_f32_e64 v5, v103, v5
	v_add_f32_e32 v18, v104, v4
	v_add_f32_e32 v19, v105, v5
	s_waitcnt lgkmcnt(0)
	v_mfma_f32_32x32x16_bf16 v[20:35], v[12:15], v[8:11], v[20:35]
	ds_read_b64_tr_b16 v[4:5], v160 offset:19456
	ds_read_b64_tr_b16 v[6:7], v160 offset:20992
	ds_read_b64_tr_b16 v[14:15], v160 offset:21056
	ds_read_b64_tr_b16 v[12:13], v160 offset:19520
	v_add_f32_e64 v18, v106, v18
	v_add_f32_e64 v19, v107, v19
	v_cvt_pk_bf16_f32 v8, v99, v101
	v_cvt_pk_bf16_f32 v9, v103, v105
	v_cvt_pk_bf16_f32 v10, v107, v109
	v_cvt_pk_bf16_f32 v11, v111, v117
	s_waitcnt lgkmcnt(2)
	s_nop 0
	v_mfma_f32_32x32x16_bf16 v[36:51], v[4:7], v[8:11], v[36:51]
	v_add_f32_e64 v4, v108, v18
	v_add_f32_e64 v5, v109, v19
	v_add_f32_e64 v4, v110, v4
	v_add_f32_e64 v5, v111, v5
	v_add_f32_e64 v4, v116, v4
	v_add_f32_e64 v5, v117, v5
	v_add_f32_e32 v4, v118, v4
	v_add_f32_e32 v5, v119, v5
	s_waitcnt lgkmcnt(0)
	v_mfma_f32_32x32x16_bf16 v[20:35], v[12:15], v[8:11], v[20:35]
	v_add_f32_e64 v18, v120, v4
	v_add_f32_e64 v19, v121, v5
	ds_read_b64_tr_b16 v[4:5], v160 offset:22528
	ds_read_b64_tr_b16 v[6:7], v160 offset:24064
	ds_read_b64_tr_b16 v[14:15], v160 offset:24128
	ds_read_b64_tr_b16 v[12:13], v160 offset:22592
	v_cvt_pk_bf16_f32 v8, v119, v121
	v_cvt_pk_bf16_f32 v9, v123, v125
	v_cvt_pk_bf16_f32 v10, v127, v129
	v_cvt_pk_bf16_f32 v11, v131, v17
	v_add_f32_e32 v18, v122, v18
	v_add_f32_e32 v19, v123, v19
	s_waitcnt lgkmcnt(2)
	v_mfma_f32_32x32x16_bf16 v[36:51], v[4:7], v[8:11], v[36:51]
	v_add_f32_e64 v4, v124, v18
	v_add_f32_e64 v5, v125, v19
	v_add_f32_e64 v4, v126, v4
	v_add_f32_e64 v5, v127, v5
	v_add_f32_e64 v4, v128, v4
	v_add_f32_e64 v5, v129, v5
	v_add_f32_e32 v4, v130, v4
	v_add_f32_e32 v5, v131, v5
	s_waitcnt lgkmcnt(0)
	v_mfma_f32_32x32x16_bf16 v[20:35], v[12:15], v[8:11], v[20:35]
	v_add_f32_e64 v4, v16, v4
	v_add_f32_e64 v5, v17, v5
	v_add_f32_e32 v1, v4, v5
	v_add_f32_e32 v161, 0, v1
	s_branch .LBB0_454

; DI float ex2(float x) { return __builtin_amdgcn_exp2f(x); }
; DI void mla_item(const P& p, char* smem, int b, int hd, int q0, bool samp) {
;     ...
;       if (redo) {
;         float mx = fmaxf(s[0][0], s[1][0]);
; #pragma unroll
;         for (int i = 1; i < 16; ++i) mx = fmaxf(mx, fmaxf(s[0][i], s[1][i]));
;         mx = fmaxf(mx, __shfl_xor(mx, 32));
;         const float up = (kb == 0) ? mx : fmaxf(mx, 0.f);
;         const float alpha = (kb == 0) ? 0.f : ex2(-up);
;         lsum *= alpha;
; #pragma unroll
;         for (int i = 0; i < 16; ++i) { o[0][i] *= alpha; o[1][i] *= alpha; }
;         mrun = (kb == 0) ? mx : mrun + up;
;         ps0 = 0.f; ps1 = 0.f;
; #pragma unroll
;         for (int i = 0; i < 16; ++i) { e[0][i] = ex2(s[0][i] - up); e[1][i] = ex2(s[1][i] - up); ps0 += e[0][i]; ps1 += e[1][i]; }
;       }
;       lsum += ps0 + ps1;
.LBB0_455:
	v_max_f32_e32 v1, v5, v5
	v_max_f32_e32 v118, v53, v53
	v_max_f32_e32 v1, v118, v1
	v_max_f32_e32 v118, v6, v6
	v_max_f32_e32 v119, v54, v54
	v_max_f32_e32 v118, v119, v118
	v_max_f32_e32 v119, v7, v7
	v_max_f32_e32 v120, v55, v55
	v_max3_f32 v1, v52, v4, v1
	v_max_f32_e32 v119, v120, v119
	v_max3_f32 v1, v1, v118, v119
	v_max_f32_e32 v118, v8, v8
	v_max_f32_e32 v119, v56, v56
	v_max_f32_e32 v118, v119, v118
	v_max_f32_e32 v119, v9, v9
	v_max_f32_e32 v120, v57, v57
	v_max_f32_e32 v119, v120, v119
	v_max3_f32 v1, v1, v118, v119
	v_max_f32_e32 v118, v10, v10
	v_max_f32_e32 v119, v58, v58
	v_max_f32_e32 v118, v119, v118
	v_max_f32_e32 v119, v11, v11
	v_max_f32_e32 v120, v59, v59
	v_max_f32_e32 v119, v120, v119
	v_max3_f32 v1, v1, v118, v119
	v_max_f32_e32 v118, v12, v12
	v_max_f32_e32 v119, v60, v60
	v_max_f32_e32 v118, v119, v118
	v_max_f32_e32 v119, v13, v13
	v_max_f32_e32 v120, v61, v61
	v_max_f32_e32 v119, v120, v119
	v_max3_f32 v1, v1, v118, v119
	v_max_f32_e32 v118, v14, v14
	v_max_f32_e32 v119, v62, v62
	v_max_f32_e32 v118, v119, v118
	v_max_f32_e32 v119, v15, v15
	v_max_f32_e32 v120, v63, v63
	v_max_f32_e32 v119, v120, v119
	v_max3_f32 v1, v1, v118, v119
	v_max_f32_e32 v118, v16, v16
	v_max_f32_e32 v119, v64, v64
	v_max_f32_e32 v118, v119, v118
	v_max_f32_e32 v119, v17, v17
	v_max_f32_e32 v120, v65, v65
	v_max_f32_e32 v119, v120, v119
	v_max3_f32 v1, v1, v118, v119
	v_max_f32_e32 v118, v18, v18
	v_max_f32_e32 v119, v66, v66
	v_max_f32_e32 v118, v119, v118
	v_max_f32_e32 v119, v19, v19
	v_max_f32_e32 v120, v67, v67
	v_max_f32_e32 v119, v120, v119
	v_max3_f32 v1, v1, v118, v119
	v_and_b32_e32 v119, 64, v154
	v_xor_b32_e32 v118, 32, v154
	v_add_u32_e32 v119, 64, v119
	v_cmp_lt_i32_e32 vcc, v118, v119
	s_nop 1
	v_cndmask_b32_e32 v118, v154, v118, vcc
	v_lshlrev_b32_e32 v118, 2, v118
	ds_bpermute_b32 v118, v118, v1
	s_waitcnt lgkmcnt(0)
	v_max3_f32 v1, v1, v118, 0
	v_sub_f32_e32 v4, v4, v1
	v_exp_f32_e32 v119, v4
	v_sub_f32_e32 v4, v53, v1
	v_exp_f32_e32 v120, v4
	v_sub_f32_e32 v4, v5, v1
	v_exp_f32_e32 v121, v4
	v_sub_f32_e32 v4, v54, v1
	v_exp_f32_e32 v122, v4
	v_sub_f32_e32 v4, v6, v1
	v_sub_f32_e32 v6, v58, v1
	v_exp_f32_e32 v144, v6
	v_sub_f32_e32 v6, v10, v1
	v_exp_f32_e32 v123, v4
	v_sub_f32_e32 v4, v55, v1
	v_exp_f32_e32 v145, v6
	v_sub_f32_e32 v6, v59, v1
	v_sub_f32_e32 v52, v52, v1
	v_exp_f32_e32 v124, v4
	v_sub_f32_e32 v4, v7, v1
	v_exp_f32_e32 v146, v6
	v_sub_f32_e32 v6, v11, v1
	v_exp_f32_e32 v118, v52
	v_exp_f32_e32 v125, v4
	v_sub_f32_e32 v4, v56, v1
	v_exp_f32_e32 v147, v6
	v_sub_f32_e32 v6, v60, v1
	v_exp_f32_e32 v126, v4
	v_sub_f32_e32 v4, v8, v1
	v_exp_f32_e32 v130, v6
	v_sub_f32_e32 v6, v12, v1
	v_exp_f32_e32 v127, v4
	v_sub_f32_e32 v4, v57, v1
	v_exp_f32_e32 v131, v6
	v_sub_f32_e32 v6, v61, v1
	v_exp_f32_e32 v128, v4
	v_sub_f32_e32 v4, v9, v1
	v_exp_f32_e32 v132, v6
	v_sub_f32_e32 v6, v13, v1
	v_exp_f32_e32 v129, v4
	v_add_f32_e32 v4, 0, v118
	v_add_f32_e32 v5, 0, v119
	v_exp_f32_e32 v133, v6
	v_sub_f32_e32 v6, v62, v1
	v_add_f32_e32 v4, v120, v4
	v_add_f32_e32 v5, v121, v5
	v_exp_f32_e32 v134, v6
	v_sub_f32_e32 v6, v14, v1
	v_add_f32_e32 v4, v122, v4
	v_add_f32_e32 v5, v123, v5
	v_exp_f32_e32 v135, v6
	v_sub_f32_e32 v6, v63, v1
	v_add_f32_e32 v4, v124, v4
	v_add_f32_e32 v5, v125, v5
	v_exp_f32_e32 v136, v6
	v_sub_f32_e32 v6, v15, v1
	v_add_f32_e32 v4, v126, v4
	v_add_f32_e32 v5, v127, v5
	v_exp_f32_e32 v137, v6
	v_sub_f32_e32 v6, v64, v1
	v_add_f32_e32 v4, v128, v4
	v_add_f32_e32 v5, v129, v5
	v_exp_f32_e32 v138, v6
	v_sub_f32_e32 v6, v16, v1
	v_exp_f32_e32 v139, v6
	v_sub_f32_e32 v6, v65, v1
	v_add_f32_e32 v4, v144, v4
	v_add_f32_e32 v5, v145, v5
	v_exp_f32_e32 v140, v6
	v_sub_f32_e32 v6, v17, v1
	v_add_f32_e32 v4, v146, v4
	v_add_f32_e32 v5, v147, v5
	v_exp_f32_e32 v141, v6
	v_sub_f32_e32 v6, v66, v1
	v_add_f32_e32 v4, v130, v4
	v_add_f32_e32 v5, v131, v5
	v_exp_f32_e32 v142, v6
	v_sub_f32_e32 v6, v18, v1
	v_add_f32_e32 v4, v132, v4
	v_add_f32_e32 v5, v133, v5
	v_exp_f32_e32 v143, v6
	v_add_f32_e32 v4, v134, v4
	v_add_f32_e32 v5, v135, v5
	v_exp_f32_e64 v182, -v1
	v_add_f32_e32 v4, v136, v4
	v_add_f32_e32 v5, v137, v5
	v_add_f32_e32 v168, v168, v1
	v_add_f32_e32 v4, v138, v4
	v_add_f32_e32 v5, v139, v5
	v_pk_mul_f32 v[34:35], v[34:35], v[182:183] op_sel_hi:[1,0]
	v_add_f32_e32 v4, v140, v4
	v_add_f32_e32 v5, v141, v5
	v_pk_mul_f32 v[32:33], v[32:33], v[182:183] op_sel_hi:[1,0]
	v_add_f32_e32 v16, v142, v4
	v_add_f32_e32 v17, v143, v5
	v_sub_f32_e32 v4, v67, v1
	v_sub_f32_e32 v1, v19, v1
	v_exp_f32_e32 v15, v1
	v_exp_f32_e32 v150, v4
	v_pk_mul_f32 v[30:31], v[30:31], v[182:183] op_sel_hi:[1,0]
	v_pk_mul_f32 v[28:29], v[28:29], v[182:183] op_sel_hi:[1,0]
	v_mov_b32_e32 v151, v15
	v_pk_mul_f32 v[26:27], v[26:27], v[182:183] op_sel_hi:[1,0]
	v_pk_mul_f32 v[24:25], v[24:25], v[182:183] op_sel_hi:[1,0]
	v_pk_mul_f32 v[22:23], v[22:23], v[182:183] op_sel_hi:[1,0]
	v_pk_mul_f32 v[20:21], v[20:21], v[182:183] op_sel_hi:[1,0]
	v_mov_b32_e32 v6, v119
	v_mov_b32_e32 v1, v121
	v_mov_b32_e32 v12, v123
	v_mov_b32_e32 v11, v125
	v_mov_b32_e32 v4, v127
	v_mov_b32_e32 v5, v129
	v_mov_b32_e32 v10, v145
	v_mov_b32_e32 v7, v147
	v_mov_b32_e32 v8, v131
	v_mov_b32_e32 v9, v133
	v_add_f32_e32 v148, v150, v16
	v_add_f32_e32 v149, v151, v17
	v_pk_mul_f32 v[50:51], v[50:51], v[182:183] op_sel_hi:[1,0]
	v_pk_mul_f32 v[48:49], v[48:49], v[182:183] op_sel_hi:[1,0]
	v_pk_mul_f32 v[46:47], v[46:47], v[182:183] op_sel_hi:[1,0]
	v_pk_mul_f32 v[44:45], v[44:45], v[182:183] op_sel_hi:[1,0]
	v_pk_mul_f32 v[42:43], v[42:43], v[182:183] op_sel_hi:[1,0]
	v_pk_mul_f32 v[40:41], v[40:41], v[182:183] op_sel_hi:[1,0]
	v_pk_mul_f32 v[38:39], v[38:39], v[182:183] op_sel_hi:[1,0]
	v_pk_mul_f32 v[36:37], v[36:37], v[182:183] op_sel_hi:[1,0]
	v_mul_f32_e32 v161, v161, v182
	v_mov_b32_e32 v14, v135
	v_mov_b32_e32 v13, v137
	v_mov_b32_e32 v16, v139
	v_mov_b32_e32 v17, v141
	v_mov_b32_e32 v18, v143

; DI float ex2(float x) { return __builtin_amdgcn_exp2f(x); }
; #define MFMA32(a, b, c) __builtin_amdgcn_mfma_f32_32x32x16_bf16((a), (b), (c), 0, 0, 0)
; DI void mla_item(const P& p, char* smem, int b, int hd, int q0, bool samp) {
;     ...
;   auto gload = [&](int kb) {
;     const size_t trow0 = samp ? (kb < 64 ? (size_t)(NTOK + b * PAST + kb * 64) : (size_t)(NTOK_P + b * 64)) : (size_t)(b * 2048 + kb * 64);
;     if (samp) {
;       const int h2 = tid >> 8, u = tid & 255;
;       const u16* base = kv + (trow0 + (u >> 3)) * 1024 + (hd + h2) * 128 + (u & 7) * 8;
;       rkn = *(const u32x4*)base; rvv = *(const u32x4*)(base + 64);
;       rkn2 = *(const u32x4*)(base + 32 * 1024); rvv2 = *(const u32x4*)(base + 32 * 1024 + 64);
;       rkr = *(const u32x4*)(krope + (trow0 + (u >> 2)) * 32 + (u & 3) * 8);
;     ...
;     if (has_next) gload(kb + 1);
;     if (active && kb < nkb_w) {
;       const char* Kt = smem + (kb & 1) * STG + hoff; const char* Vt = Kt + 64 * KS_MLA;
;       f32x16 s[2];
;       const float cinit = (kb == 0) ? 0.f : -mrun;
; #pragma unroll
;       for (int i = 0; i < 16; ++i) { s[0][i] = cinit; s[1][i] = cinit; }
;       const char* kp = Kt + l32 * KS_MLA + lh * 16;
; #pragma unroll
;       for (int ks = 0; ks < 6; ++ks) {
;         const bf16x8 a0 = *(const bf16x8*)(kp + ks * 32);
;         const bf16x8 a1 = *(const bf16x8*)(kp + 32 * KS_MLA + ks * 32);
;         s[0] = MFMA32(a0, qf[ks], s[0]);
;         s[1] = MFMA32(a1, qf[ks], s[1]);
;       }
;       f32x16 e[2];
;       float ps0 = 0.f, ps1 = 0.f;
;       bool redo = (kb == 0);
;       if (!redo) {
; #pragma unroll
;         for (int i = 0; i < 16; ++i) { e[0][i] = ex2(s[0][i]); e[1][i] = ex2(s[1][i]); ps0 += e[0][i]; ps1 += e[1][i]; }
;         redo = (__builtin_amdgcn_ballot_w64(!(ps0 + ps1 < 1e18f)) != 0ull);
;       }
.LBB0_458:
	s_ashr_i32 s65, s63, 31
	v_mov_b32_e32 v5, s65
	v_or_b32_e32 v4, s63, v113
	v_lshlrev_b64 v[4:5], 11, v[4:5]
	v_lshl_add_u64 v[4:5], v[114:115], 0, v[4:5]
	global_load_dwordx4 v[96:99], v[4:5], off
	global_load_dwordx4 v[92:95], v[4:5], off offset:128
	v_add_co_u32_e32 v4, vcc, 0x10000, v4
	s_nop 1
	v_addc_co_u32_e32 v5, vcc, 0, v5, vcc
	global_load_dwordx4 v[104:107], v[4:5], off
	global_load_dwordx4 v[100:103], v[4:5], off offset:128
	v_mov_b32_e32 v5, s65
	v_or_b32_e32 v4, s63, v169
	v_lshlrev_b64 v[4:5], 6, v[4:5]
	v_lshl_add_u64 v[4:5], v[116:117], 0, v[4:5]
	global_load_dwordx4 v[108:111], v[4:5], off
	s_and_b64 vcc, exec, s[4:5]
	s_cbranch_vccnz .LBB0_457
	s_bitcmp1_b32 s64, 0
	s_cselect_b32 s65, 0, 0xc800
	s_add_i32 s65, s62, s65
	v_add3_u32 v1, s65, v174, v112
	ds_read_b128 v[118:121], v1
	ds_read_b128 v[122:125], v1 offset:32
	v_xor_b32_e32 v4, 0x80000000, v168
	v_mov_b32_e32 v5, v4
	v_mov_b32_e32 v6, v4
	v_mov_b32_e32 v7, v4
	v_mov_b32_e32 v8, v4
	v_mov_b32_e32 v9, v4
	v_mov_b32_e32 v10, v4
	v_mov_b32_e32 v11, v4
	v_mov_b32_e32 v12, v4
	v_mov_b32_e32 v13, v4
	v_mov_b32_e32 v14, v4
	v_mov_b32_e32 v15, v4
	v_mov_b32_e32 v16, v4
	v_mov_b32_e32 v17, v4
	v_mov_b32_e32 v18, v4
	v_mov_b32_e32 v19, v4
	s_waitcnt lgkmcnt(1)
	s_nop 0
	v_mfma_f32_32x32x16_bf16 v[52:67], v[118:121], v[88:91], v[4:19]
	ds_read_b128 v[118:121], v1 offset:6656
	ds_read_b128 v[126:129], v1 offset:6688
	s_waitcnt lgkmcnt(1)
	v_mfma_f32_32x32x16_bf16 v[4:19], v[118:121], v[88:91], v[4:19]
	v_mfma_f32_32x32x16_bf16 v[52:67], v[122:125], v[84:87], v[52:67]
	ds_read_b128 v[118:121], v1 offset:64
	ds_read_b128 v[122:125], v1 offset:96
	s_waitcnt lgkmcnt(2)
	v_mfma_f32_32x32x16_bf16 v[4:19], v[126:129], v[84:87], v[4:19]
	s_waitcnt lgkmcnt(1)
	v_mfma_f32_32x32x16_bf16 v[52:67], v[118:121], v[80:83], v[52:67]
	ds_read_b128 v[118:121], v1 offset:6720
	ds_read_b128 v[126:129], v1 offset:6752
	s_waitcnt lgkmcnt(1)
	v_mfma_f32_32x32x16_bf16 v[4:19], v[118:121], v[80:83], v[4:19]
	v_mfma_f32_32x32x16_bf16 v[52:67], v[122:125], v[76:79], v[52:67]
	ds_read_b128 v[118:121], v1 offset:128
	ds_read_b128 v[122:125], v1 offset:160
	s_waitcnt lgkmcnt(2)
	v_mfma_f32_32x32x16_bf16 v[4:19], v[126:129], v[76:79], v[4:19]
	s_waitcnt lgkmcnt(1)
	v_mfma_f32_32x32x16_bf16 v[52:67], v[118:121], v[72:75], v[52:67]
	ds_read_b128 v[118:121], v1 offset:6784
	ds_read_b128 v[126:129], v1 offset:6816
	s_waitcnt lgkmcnt(1)
	v_mfma_f32_32x32x16_bf16 v[4:19], v[118:121], v[72:75], v[4:19]
	v_mfma_f32_32x32x16_bf16 v[52:67], v[122:125], v[68:71], v[52:67]
	s_waitcnt lgkmcnt(0)
	v_mfma_f32_32x32x16_bf16 v[4:19], v[126:129], v[68:71], v[4:19]
	s_nop 9
	v_exp_f32_e32 v118, v52
	v_exp_f32_e32 v120, v53
	v_exp_f32_e32 v122, v54
	v_exp_f32_e32 v124, v55
	v_exp_f32_e32 v126, v56
	v_exp_f32_e32 v128, v57
	v_exp_f32_e32 v144, v58
	v_exp_f32_e32 v119, v4
	v_exp_f32_e32 v121, v5
	v_exp_f32_e32 v123, v6
	v_exp_f32_e32 v125, v7
	v_exp_f32_e32 v127, v8
	v_add_f32_e32 v130, 0, v118
	v_add_f32_e32 v131, 0, v119
	v_exp_f32_e32 v129, v9
	v_add_f32_e32 v130, v120, v130
	v_add_f32_e32 v131, v121, v131
	v_exp_f32_e32 v145, v10
	v_add_f32_e32 v130, v122, v130
	v_add_f32_e32 v131, v123, v131
	v_exp_f32_e32 v146, v59
	v_add_f32_e32 v130, v124, v130
	v_add_f32_e32 v131, v125, v131
	v_exp_f32_e32 v147, v11
	v_add_f32_e32 v130, v126, v130
	v_add_f32_e32 v131, v127, v131
	v_exp_f32_e32 v132, v61
	v_add_f32_e32 v148, v128, v130
	v_add_f32_e32 v149, v129, v131
	v_exp_f32_e32 v130, v60
	v_exp_f32_e32 v131, v12
	v_exp_f32_e32 v133, v13
	v_exp_f32_e32 v134, v62
	v_exp_f32_e32 v135, v14
	v_add_f32_e32 v148, v144, v148
	v_add_f32_e32 v149, v145, v149
	v_exp_f32_e32 v136, v63
	v_exp_f32_e32 v137, v15
	v_add_f32_e32 v148, v146, v148
	v_add_f32_e32 v149, v147, v149
	v_exp_f32_e32 v138, v64
	v_exp_f32_e32 v139, v16
	v_add_f32_e32 v148, v130, v148
	v_add_f32_e32 v149, v131, v149
	v_exp_f32_e32 v140, v65
	v_exp_f32_e32 v141, v17
	v_add_f32_e32 v148, v132, v148
	v_add_f32_e32 v149, v133, v149
	v_exp_f32_e32 v142, v66
	v_exp_f32_e32 v143, v18
	v_add_f32_e32 v148, v134, v148
	v_add_f32_e32 v149, v135, v149
	v_exp_f32_e32 v150, v67
	v_exp_f32_e32 v151, v19
	v_add_f32_e32 v148, v136, v148
	v_add_f32_e32 v149, v137, v149
	s_nop 0
	v_add_f32_e32 v148, v138, v148
	v_add_f32_e32 v149, v139, v149
	s_nop 0
	v_add_f32_e32 v148, v140, v148
	v_add_f32_e32 v149, v141, v149
	s_nop 0
	v_add_f32_e32 v148, v142, v148
	v_add_f32_e32 v149, v143, v149
	s_nop 0
	v_add_f32_e32 v148, v150, v148
	v_add_f32_e32 v149, v151, v149
	s_nop 0
	v_add_f32_e32 v1, v148, v149
	v_cmp_ngt_f32_e32 vcc, s79, v1
	s_cbranch_vccnz .LBB0_455
	v_mov_b32_e32 v6, v119
	v_mov_b32_e32 v1, v121
	v_mov_b32_e32 v12, v123
	v_mov_b32_e32 v11, v125
	v_mov_b32_e32 v4, v127
	v_mov_b32_e32 v5, v129
	v_mov_b32_e32 v10, v145
	v_mov_b32_e32 v7, v147
	v_mov_b32_e32 v8, v131
	v_mov_b32_e32 v9, v133
	v_mov_b32_e32 v14, v135
	v_mov_b32_e32 v13, v137
	v_mov_b32_e32 v16, v139
	v_mov_b32_e32 v17, v141
	v_mov_b32_e32 v18, v143
	v_mov_b32_e32 v15, v151
	s_branch .LBB0_456
; DI float ex2(float x) { return __builtin_amdgcn_exp2f(x); }
; #define MFMA32(a, b, c) __builtin_amdgcn_mfma_f32_32x32x16_bf16((a), (b), (c), 0, 0, 0)
; DI void mla_item(const P& p, char* smem, int b, int hd, int q0, bool samp) {
;     ...
;   auto gload = [&](int kb) {
;     const size_t trow0 = samp ? (kb < 64 ? (size_t)(NTOK + b * PAST + kb * 64) : (size_t)(NTOK_P + b * 64)) : (size_t)(b * 2048 + kb * 64);
;     if (samp) {
;       const int h2 = tid >> 8, u = tid & 255;
;       const u16* base = kv + (trow0 + (u >> 3)) * 1024 + (hd + h2) * 128 + (u & 7) * 8;
;       rkn = *(const u32x4*)base; rvv = *(const u32x4*)(base + 64);
;       rkn2 = *(const u32x4*)(base + 32 * 1024); rvv2 = *(const u32x4*)(base + 32 * 1024 + 64);
;       rkr = *(const u32x4*)(krope + (trow0 + (u >> 2)) * 32 + (u & 3) * 8);
;     ...
;     if (has_next) gload(kb + 1);
;     if (active && kb < nkb_w) {
;       const char* Kt = smem + (kb & 1) * STG + hoff; const char* Vt = Kt + 64 * KS_MLA;
;       f32x16 s[2];
;       const float cinit = (kb == 0) ? 0.f : -mrun;
; #pragma unroll
;       for (int i = 0; i < 16; ++i) { s[0][i] = cinit; s[1][i] = cinit; }
;       const char* kp = Kt + l32 * KS_MLA + lh * 16;
; #pragma unroll
;       for (int ks = 0; ks < 6; ++ks) {
;         const bf16x8 a0 = *(const bf16x8*)(kp + ks * 32);
;         const bf16x8 a1 = *(const bf16x8*)(kp + 32 * KS_MLA + ks * 32);
;         s[0] = MFMA32(a0, qf[ks], s[0]);
;         s[1] = MFMA32(a1, qf[ks], s[1]);
;       }
;       f32x16 e[2];
;       float ps0 = 0.f, ps1 = 0.f;
;       bool redo = (kb == 0);
;       if (!redo) {
; #pragma unroll
;         for (int i = 0; i < 16; ++i) { e[0][i] = ex2(s[0][i]); e[1][i] = ex2(s[1][i]); ps0 += e[0][i]; ps1 += e[1][i]; }
;         redo = (__builtin_amdgcn_ballot_w64(!(ps0 + ps1 < 1e18f)) != 0ull);
;       }
.LBB0_461:
	v_mov_b32_e32 v5, s61
	v_or_b32_e32 v4, s60, v113
	v_lshlrev_b64 v[4:5], 11, v[4:5]
	v_lshl_add_u64 v[4:5], v[114:115], 0, v[4:5]
	global_load_dwordx4 v[96:99], v[4:5], off
	global_load_dwordx4 v[92:95], v[4:5], off offset:128
	v_add_co_u32_e32 v4, vcc, 0x10000, v4
	s_nop 1
	v_addc_co_u32_e32 v5, vcc, 0, v5, vcc
	global_load_dwordx4 v[104:107], v[4:5], off
	global_load_dwordx4 v[100:103], v[4:5], off offset:128
	v_mov_b32_e32 v5, s61
	v_or_b32_e32 v4, s60, v169
	v_lshlrev_b64 v[4:5], 6, v[4:5]
	v_lshl_add_u64 v[4:5], v[116:117], 0, v[4:5]
	global_load_dwordx4 v[108:111], v[4:5], off
	s_and_b64 vcc, exec, s[4:5]
	s_cbranch_vccnz .LBB0_466
	ds_read_b128 v[112:115], v162 offset:51200
	ds_read_b128 v[116:119], v162 offset:51232
	v_xor_b32_e32 v4, 0x80000000, v168
	v_mov_b32_e32 v5, v4
	v_mov_b32_e32 v6, v4
	v_mov_b32_e32 v7, v4
	v_mov_b32_e32 v8, v4
	v_mov_b32_e32 v9, v4
	v_mov_b32_e32 v10, v4
	v_mov_b32_e32 v11, v4
	v_mov_b32_e32 v12, v4
	v_mov_b32_e32 v13, v4
	v_mov_b32_e32 v14, v4
	v_mov_b32_e32 v15, v4
	v_mov_b32_e32 v16, v4
	v_mov_b32_e32 v17, v4
	v_mov_b32_e32 v18, v4
	v_mov_b32_e32 v19, v4
	s_waitcnt lgkmcnt(1)
	s_nop 0
	v_mfma_f32_32x32x16_bf16 v[52:67], v[112:115], v[88:91], v[4:19]
	ds_read_b128 v[112:115], v162 offset:57856
	ds_read_b128 v[120:123], v162 offset:57888
	s_waitcnt lgkmcnt(1)
	v_mfma_f32_32x32x16_bf16 v[4:19], v[112:115], v[88:91], v[4:19]
	v_mfma_f32_32x32x16_bf16 v[52:67], v[116:119], v[84:87], v[52:67]
	ds_read_b128 v[112:115], v162 offset:51264
	ds_read_b128 v[116:119], v162 offset:51296
	s_waitcnt lgkmcnt(2)
	v_mfma_f32_32x32x16_bf16 v[4:19], v[120:123], v[84:87], v[4:19]
	s_waitcnt lgkmcnt(1)
	v_mfma_f32_32x32x16_bf16 v[52:67], v[112:115], v[80:83], v[52:67]
	ds_read_b128 v[112:115], v162 offset:57920
	ds_read_b128 v[120:123], v162 offset:57952
	s_waitcnt lgkmcnt(1)
	v_mfma_f32_32x32x16_bf16 v[4:19], v[112:115], v[80:83], v[4:19]
	v_mfma_f32_32x32x16_bf16 v[52:67], v[116:119], v[76:79], v[52:67]
	ds_read_b128 v[112:115], v162 offset:51328
	ds_read_b128 v[116:119], v162 offset:51360
	s_waitcnt lgkmcnt(2)
	v_mfma_f32_32x32x16_bf16 v[4:19], v[120:123], v[76:79], v[4:19]
	s_waitcnt lgkmcnt(1)
	v_mfma_f32_32x32x16_bf16 v[52:67], v[112:115], v[72:75], v[52:67]
	ds_read_b128 v[112:115], v162 offset:57984
	ds_read_b128 v[120:123], v162 offset:58016
	s_waitcnt lgkmcnt(1)
	v_mfma_f32_32x32x16_bf16 v[4:19], v[112:115], v[72:75], v[4:19]
	v_mfma_f32_32x32x16_bf16 v[52:67], v[116:119], v[68:71], v[52:67]
	s_waitcnt lgkmcnt(0)
	v_mfma_f32_32x32x16_bf16 v[4:19], v[120:123], v[68:71], v[4:19]
	s_nop 9
	v_exp_f32_e32 v112, v52
	v_exp_f32_e32 v114, v53
	v_exp_f32_e32 v116, v54
	v_exp_f32_e32 v118, v55
	v_exp_f32_e32 v122, v56
	v_exp_f32_e32 v126, v57
	v_exp_f32_e32 v138, v58
	v_exp_f32_e32 v113, v4
	v_exp_f32_e32 v115, v5
	v_exp_f32_e32 v117, v6
	v_exp_f32_e32 v119, v7
	v_exp_f32_e32 v123, v8
	v_add_f32_e32 v120, 0, v112
	v_add_f32_e32 v121, 0, v113
	v_exp_f32_e32 v127, v9
	v_add_f32_e32 v120, v114, v120
	v_add_f32_e32 v121, v115, v121
	v_exp_f32_e32 v139, v10
	v_add_f32_e32 v120, v116, v120
	v_add_f32_e32 v121, v117, v121
	v_exp_f32_e32 v140, v59
	v_add_f32_e32 v120, v118, v120
	v_add_f32_e32 v121, v119, v121
	v_exp_f32_e32 v141, v11
	v_add_f32_e32 v120, v122, v120
	v_add_f32_e32 v121, v123, v121
	v_exp_f32_e32 v124, v61
	v_add_f32_e32 v144, v126, v120
	v_add_f32_e32 v145, v127, v121
	v_exp_f32_e32 v120, v60
	v_exp_f32_e32 v121, v12
	v_exp_f32_e32 v125, v13
	v_exp_f32_e32 v128, v62
	v_exp_f32_e32 v129, v14
	v_add_f32_e32 v144, v138, v144
	v_add_f32_e32 v145, v139, v145
	v_exp_f32_e32 v130, v63
	v_exp_f32_e32 v131, v15
	v_add_f32_e32 v144, v140, v144
	v_add_f32_e32 v145, v141, v145
	v_exp_f32_e32 v132, v64
	v_exp_f32_e32 v133, v16
	v_add_f32_e32 v144, v120, v144
	v_add_f32_e32 v145, v121, v145
	v_exp_f32_e32 v134, v65
	v_exp_f32_e32 v135, v17
	v_add_f32_e32 v144, v124, v144
	v_add_f32_e32 v145, v125, v145
	v_exp_f32_e32 v136, v66
	v_exp_f32_e32 v137, v18
	v_add_f32_e32 v144, v128, v144
	v_add_f32_e32 v145, v129, v145
	v_exp_f32_e32 v142, v67
	v_exp_f32_e32 v143, v19
	v_add_f32_e32 v144, v130, v144
	v_add_f32_e32 v145, v131, v145
	s_nop 0
	v_add_f32_e32 v144, v132, v144
	v_add_f32_e32 v145, v133, v145
	s_nop 0
	v_add_f32_e32 v144, v134, v144
	v_add_f32_e32 v145, v135, v145
	s_nop 0
	v_add_f32_e32 v144, v136, v144
	v_add_f32_e32 v145, v137, v145
	s_nop 0
	v_add_f32_e32 v144, v142, v144
	v_add_f32_e32 v145, v143, v145
	s_nop 0
	v_add_f32_e32 v1, v144, v145
	v_cmp_ngt_f32_e32 vcc, s79, v1
	s_cbranch_vccz .LBB0_464
; DI float ex2(float x) { return __builtin_amdgcn_exp2f(x); }
; DI void mla_item(const P& p, char* smem, int b, int hd, int q0, bool samp) {
;     ...
;       if (redo) {
;         float mx = fmaxf(s[0][0], s[1][0]);
; #pragma unroll
;         for (int i = 1; i < 16; ++i) mx = fmaxf(mx, fmaxf(s[0][i], s[1][i]));
;         mx = fmaxf(mx, __shfl_xor(mx, 32));
;         const float up = (kb == 0) ? mx : fmaxf(mx, 0.f);
;         const float alpha = (kb == 0) ? 0.f : ex2(-up);
;         lsum *= alpha;
; #pragma unroll
;         for (int i = 0; i < 16; ++i) { o[0][i] *= alpha; o[1][i] *= alpha; }
;         mrun = (kb == 0) ? mx : mrun + up;
;         ps0 = 0.f; ps1 = 0.f;
; #pragma unroll
;         for (int i = 0; i < 16; ++i) { e[0][i] = ex2(s[0][i] - up); e[1][i] = ex2(s[1][i] - up); ps0 += e[0][i]; ps1 += e[1][i]; }
;       }
;       lsum += ps0 + ps1;
	v_max_f32_e32 v1, v5, v5
	v_max_f32_e32 v2, v53, v53
	v_max_f32_e32 v1, v2, v1
	v_max_f32_e32 v2, v6, v6
	v_max_f32_e32 v112, v54, v54
	v_max_f32_e32 v2, v112, v2
	v_max_f32_e32 v112, v7, v7
	v_max_f32_e32 v113, v55, v55
	v_max3_f32 v1, v52, v4, v1
	v_max_f32_e32 v112, v113, v112
	v_max3_f32 v1, v1, v2, v112
	v_max_f32_e32 v2, v8, v8
	v_max_f32_e32 v112, v56, v56
	v_max_f32_e32 v2, v112, v2
	v_max_f32_e32 v112, v9, v9
	v_max_f32_e32 v113, v57, v57
	v_max_f32_e32 v112, v113, v112
	v_max3_f32 v1, v1, v2, v112
	v_max_f32_e32 v2, v10, v10
	v_max_f32_e32 v112, v58, v58
	v_max_f32_e32 v2, v112, v2
	v_max_f32_e32 v112, v11, v11
	v_max_f32_e32 v113, v59, v59
	v_max_f32_e32 v112, v113, v112
	v_max3_f32 v1, v1, v2, v112
	v_max_f32_e32 v2, v12, v12
	v_max_f32_e32 v112, v60, v60
	v_max_f32_e32 v2, v112, v2
	v_max_f32_e32 v112, v13, v13
	v_max_f32_e32 v113, v61, v61
	v_max_f32_e32 v112, v113, v112
	v_max3_f32 v1, v1, v2, v112
	v_max_f32_e32 v2, v14, v14
	v_max_f32_e32 v112, v62, v62
	v_max_f32_e32 v2, v112, v2
	v_max_f32_e32 v112, v15, v15
	v_max_f32_e32 v113, v63, v63
	v_max_f32_e32 v112, v113, v112
	v_max3_f32 v1, v1, v2, v112
	v_max_f32_e32 v2, v16, v16
	v_max_f32_e32 v112, v64, v64
	v_max_f32_e32 v2, v112, v2
	v_max_f32_e32 v112, v17, v17
	v_max_f32_e32 v113, v65, v65
	v_max_f32_e32 v112, v113, v112
	v_max3_f32 v1, v1, v2, v112
	v_max_f32_e32 v2, v18, v18
	v_max_f32_e32 v112, v66, v66
	v_max_f32_e32 v2, v112, v2
	v_max_f32_e32 v112, v19, v19
	v_max_f32_e32 v113, v67, v67
	v_max_f32_e32 v112, v113, v112
	v_max3_f32 v1, v1, v2, v112
	v_and_b32_e32 v112, 64, v154
	v_xor_b32_e32 v2, 32, v154
	v_add_u32_e32 v112, 64, v112
	v_cmp_lt_i32_e32 vcc, v2, v112
	s_nop 1
	v_cndmask_b32_e32 v2, v154, v2, vcc
	v_lshlrev_b32_e32 v2, 2, v2
	ds_bpermute_b32 v2, v2, v1
	s_waitcnt lgkmcnt(0)
	v_max3_f32 v1, v1, v2, 0
	v_sub_f32_e32 v2, v52, v1
	v_exp_f32_e32 v112, v2
	v_sub_f32_e32 v2, v4, v1
	v_exp_f32_e32 v113, v2
	v_sub_f32_e32 v2, v53, v1
	v_exp_f32_e32 v114, v2
	v_sub_f32_e32 v2, v5, v1
	v_exp_f32_e32 v115, v2
	v_sub_f32_e32 v2, v54, v1
	v_exp_f32_e32 v116, v2
	v_sub_f32_e32 v2, v6, v1
	v_exp_f32_e32 v117, v2
	v_sub_f32_e32 v2, v55, v1
	v_exp_f32_e32 v118, v2
	v_sub_f32_e32 v2, v7, v1
	v_exp_f32_e32 v119, v2
	v_sub_f32_e32 v2, v56, v1
	v_exp_f32_e32 v122, v2
	v_sub_f32_e32 v2, v8, v1
	v_exp_f32_e32 v123, v2
	v_sub_f32_e32 v2, v57, v1
	v_exp_f32_e32 v126, v2
	v_sub_f32_e32 v2, v9, v1
	v_exp_f32_e32 v127, v2
	v_sub_f32_e32 v2, v58, v1
	v_exp_f32_e32 v138, v2
	v_sub_f32_e32 v2, v10, v1
	v_exp_f32_e32 v139, v2
	v_sub_f32_e32 v2, v59, v1
	v_exp_f32_e32 v140, v2
	v_sub_f32_e32 v2, v11, v1
	v_exp_f32_e32 v141, v2
	v_sub_f32_e32 v2, v60, v1
	v_exp_f32_e32 v120, v2
	v_sub_f32_e32 v2, v12, v1
	v_exp_f32_e32 v121, v2
	v_sub_f32_e32 v2, v61, v1
	v_exp_f32_e32 v124, v2
	v_sub_f32_e32 v2, v13, v1
	v_exp_f32_e32 v125, v2
	v_sub_f32_e32 v2, v62, v1
	v_add_f32_e32 v4, 0, v112
	v_add_f32_e32 v5, 0, v113
	v_exp_f32_e32 v128, v2
	v_sub_f32_e32 v2, v14, v1
	v_add_f32_e32 v4, v114, v4
	v_add_f32_e32 v5, v115, v5
	v_exp_f32_e32 v129, v2
	v_sub_f32_e32 v2, v63, v1
	v_add_f32_e32 v4, v116, v4
	v_add_f32_e32 v5, v117, v5
	v_exp_f32_e32 v130, v2
	v_sub_f32_e32 v2, v15, v1
	v_add_f32_e32 v4, v118, v4
	v_add_f32_e32 v5, v119, v5
	v_exp_f32_e32 v131, v2
	v_sub_f32_e32 v2, v64, v1
	v_add_f32_e32 v4, v122, v4
	v_add_f32_e32 v5, v123, v5
	v_exp_f32_e32 v132, v2
	v_sub_f32_e32 v2, v16, v1
	v_add_f32_e32 v4, v126, v4
	v_add_f32_e32 v5, v127, v5
	v_exp_f32_e32 v133, v2
	v_sub_f32_e32 v2, v65, v1
	v_exp_f32_e32 v134, v2
	v_sub_f32_e32 v2, v17, v1
	v_add_f32_e32 v4, v138, v4
	v_add_f32_e32 v5, v139, v5
	v_exp_f32_e32 v135, v2
	v_sub_f32_e32 v2, v66, v1
	v_add_f32_e32 v4, v140, v4
	v_add_f32_e32 v5, v141, v5
	v_exp_f32_e32 v136, v2
	v_sub_f32_e32 v2, v18, v1
	v_add_f32_e32 v4, v120, v4
	v_add_f32_e32 v5, v121, v5
	v_exp_f32_e64 v146, -v1
	v_add_f32_e32 v168, v168, v1
	v_exp_f32_e32 v137, v2
	v_add_f32_e32 v4, v124, v4
	v_add_f32_e32 v5, v125, v5
	v_sub_f32_e32 v2, v67, v1
	v_sub_f32_e32 v1, v19, v1
	v_add_f32_e32 v4, v128, v4
	v_add_f32_e32 v5, v129, v5
	v_exp_f32_e32 v15, v1
	v_add_f32_e32 v4, v130, v4
	v_add_f32_e32 v5, v131, v5
	v_exp_f32_e32 v142, v2
	v_add_f32_e32 v4, v132, v4
	v_add_f32_e32 v5, v133, v5
	v_mov_b32_e32 v143, v15
	v_add_f32_e32 v4, v134, v4
	v_add_f32_e32 v5, v135, v5
	v_pk_mul_f32 v[34:35], v[34:35], v[146:147] op_sel_hi:[1,0]
	v_add_f32_e32 v12, v136, v4
	v_add_f32_e32 v13, v137, v5
	v_pk_mul_f32 v[32:33], v[32:33], v[146:147] op_sel_hi:[1,0]
	v_pk_mul_f32 v[30:31], v[30:31], v[146:147] op_sel_hi:[1,0]
	v_pk_mul_f32 v[28:29], v[28:29], v[146:147] op_sel_hi:[1,0]
	v_pk_mul_f32 v[26:27], v[26:27], v[146:147] op_sel_hi:[1,0]
	v_pk_mul_f32 v[24:25], v[24:25], v[146:147] op_sel_hi:[1,0]
	v_pk_mul_f32 v[22:23], v[22:23], v[146:147] op_sel_hi:[1,0]
	v_pk_mul_f32 v[20:21], v[20:21], v[146:147] op_sel_hi:[1,0]
	v_mov_b32_e32 v2, v113
	v_mov_b32_e32 v1, v115
	v_mov_b32_e32 v4, v117
	v_mov_b32_e32 v5, v119
	v_mov_b32_e32 v6, v123
	v_mov_b32_e32 v7, v127
	v_mov_b32_e32 v10, v139
	v_mov_b32_e32 v11, v141
	v_mov_b32_e32 v8, v121
	v_mov_b32_e32 v9, v125
	v_add_f32_e32 v144, v142, v12
	v_add_f32_e32 v145, v143, v13
	v_pk_mul_f32 v[50:51], v[50:51], v[146:147] op_sel_hi:[1,0]
	v_pk_mul_f32 v[48:49], v[48:49], v[146:147] op_sel_hi:[1,0]
	v_pk_mul_f32 v[46:47], v[46:47], v[146:147] op_sel_hi:[1,0]
	v_pk_mul_f32 v[44:45], v[44:45], v[146:147] op_sel_hi:[1,0]
	v_pk_mul_f32 v[42:43], v[42:43], v[146:147] op_sel_hi:[1,0]
	v_pk_mul_f32 v[40:41], v[40:41], v[146:147] op_sel_hi:[1,0]
	v_pk_mul_f32 v[38:39], v[38:39], v[146:147] op_sel_hi:[1,0]
	v_pk_mul_f32 v[36:37], v[36:37], v[146:147] op_sel_hi:[1,0]
	v_mul_f32_e32 v161, v161, v146
	v_mov_b32_e32 v12, v129
	v_mov_b32_e32 v13, v131
	v_mov_b32_e32 v14, v133
	v_mov_b32_e32 v17, v135
	v_mov_b32_e32 v16, v137
	s_branch .LBB0_465

; DI float ex2(float x) { return __builtin_amdgcn_exp2f(x); }
; #define MFMA32(a, b, c) __builtin_amdgcn_mfma_f32_32x32x16_bf16((a), (b), (c), 0, 0, 0)
; DI void mla_item(const P& p, char* smem, int b, int hd, int q0, bool samp) {
;     ...
;   auto lstore = [&](int buf) {
;     if (samp) {
;       const int h2 = tid >> 8, u = tid & 255;
;       char* Kt = smem + buf * STG + h2 * MLA_STAGE; char* Vt = Kt + 64 * KS_MLA;
;       *(u32x4*)(Kt + (u >> 3) * KS_MLA + (u & 7) * 16) = rkn;
;       *(u32x4*)(Kt + (32 + (u >> 3)) * KS_MLA + (u & 7) * 16) = rkn2;
;       *(u32x4*)(Vt + (u >> 3) * VS + (u & 7) * 16) = rvv;
;       *(u32x4*)(Vt + (32 + (u >> 3)) * VS + (u & 7) * 16) = rvv2;
;       *(u32x4*)(Kt + (u >> 2) * KS_MLA + 128 + (u & 3) * 16) = rkr;
;     } else {
;     ...
;       const char* Kt = smem + (kb & 1) * STG + hoff; const char* Vt = Kt + 64 * KS_MLA;
;       f32x16 s[2];
;       const float cinit = (kb == 0) ? 0.f : -mrun;
; #pragma unroll
;       for (int i = 0; i < 16; ++i) { s[0][i] = cinit; s[1][i] = cinit; }
;       const char* kp = Kt + l32 * KS_MLA + lh * 16;
; #pragma unroll
;       for (int ks = 0; ks < 6; ++ks) {
;         const bf16x8 a0 = *(const bf16x8*)(kp + ks * 32);
;         const bf16x8 a1 = *(const bf16x8*)(kp + 32 * KS_MLA + ks * 32);
;         s[0] = MFMA32(a0, qf[ks], s[0]);
;         s[1] = MFMA32(a1, qf[ks], s[1]);
;       }
;       f32x16 e[2];
;       float ps0 = 0.f, ps1 = 0.f;
;       bool redo = (kb == 0);
;       if (!redo) {
; #pragma unroll
;         for (int i = 0; i < 16; ++i) { e[0][i] = ex2(s[0][i]); e[1][i] = ex2(s[1][i]); ps0 += e[0][i]; ps1 += e[1][i]; }
;         redo = (__builtin_amdgcn_ballot_w64(!(ps0 + ps1 < 1e18f)) != 0ull);
;       }
;     ...
;     if (has_next) lstore((kb + 1) & 1);
;     __syncthreads();
.LBB0_466:
	s_and_b64 vcc, exec, s[4:5]
	s_waitcnt vmcnt(4)
	ds_write_b128 v163, v[96:99]
	s_waitcnt vmcnt(2)
	ds_write_b128 v164, v[104:107]
	ds_write_b128 v165, v[92:95] offset:13312
	s_waitcnt vmcnt(1)
	ds_write_b128 v166, v[100:103] offset:13312
	s_waitcnt vmcnt(0)
	ds_write_b128 v167, v[108:111] offset:128
	s_waitcnt lgkmcnt(0)
	s_barrier
	s_cbranch_vccnz .LBB0_471
	ds_read_b128 v[92:95], v162
	ds_read_b128 v[96:99], v162 offset:32
	v_xor_b32_e32 v4, 0x80000000, v168
	v_mov_b32_e32 v5, v4
	v_mov_b32_e32 v6, v4
	v_mov_b32_e32 v7, v4
	v_mov_b32_e32 v8, v4
	v_mov_b32_e32 v9, v4
	v_mov_b32_e32 v10, v4
	v_mov_b32_e32 v11, v4
	v_mov_b32_e32 v12, v4
	v_mov_b32_e32 v13, v4
	v_mov_b32_e32 v14, v4
	v_mov_b32_e32 v15, v4
	v_mov_b32_e32 v16, v4
	v_mov_b32_e32 v17, v4
	v_mov_b32_e32 v18, v4
	v_mov_b32_e32 v19, v4
	s_waitcnt lgkmcnt(1)
	s_nop 0
	v_mfma_f32_32x32x16_bf16 v[52:67], v[92:95], v[88:91], v[4:19]
	ds_read_b128 v[92:95], v162 offset:6656
	ds_read_b128 v[100:103], v162 offset:6688
	s_waitcnt lgkmcnt(1)
	v_mfma_f32_32x32x16_bf16 v[4:19], v[92:95], v[88:91], v[4:19]
	v_mfma_f32_32x32x16_bf16 v[52:67], v[96:99], v[84:87], v[52:67]
	s_waitcnt lgkmcnt(0)
	v_mfma_f32_32x32x16_bf16 v[4:19], v[100:103], v[84:87], v[4:19]
	ds_read_b128 v[84:87], v162 offset:64
	ds_read_b128 v[88:91], v162 offset:96
	s_waitcnt lgkmcnt(1)
	v_mfma_f32_32x32x16_bf16 v[52:67], v[84:87], v[80:83], v[52:67]
	ds_read_b128 v[84:87], v162 offset:6720
	ds_read_b128 v[92:95], v162 offset:6752
	s_waitcnt lgkmcnt(1)
	v_mfma_f32_32x32x16_bf16 v[4:19], v[84:87], v[80:83], v[4:19]
	v_mfma_f32_32x32x16_bf16 v[52:67], v[88:91], v[76:79], v[52:67]
	s_waitcnt lgkmcnt(0)
	v_mfma_f32_32x32x16_bf16 v[4:19], v[92:95], v[76:79], v[4:19]
	ds_read_b128 v[76:79], v162 offset:128
	ds_read_b128 v[80:83], v162 offset:160
	s_waitcnt lgkmcnt(1)
	v_mfma_f32_32x32x16_bf16 v[52:67], v[76:79], v[72:75], v[52:67]
	ds_read_b128 v[76:79], v162 offset:6784
	ds_read_b128 v[84:87], v162 offset:6816
	s_waitcnt lgkmcnt(1)
	v_mfma_f32_32x32x16_bf16 v[4:19], v[76:79], v[72:75], v[4:19]
	v_mfma_f32_32x32x16_bf16 v[52:67], v[80:83], v[68:71], v[52:67]
	s_waitcnt lgkmcnt(0)
	v_mfma_f32_32x32x16_bf16 v[4:19], v[84:87], v[68:71], v[4:19]
	s_nop 9
	v_exp_f32_e32 v72, v52
	v_exp_f32_e32 v68, v53
	v_exp_f32_e32 v70, v54
	v_exp_f32_e32 v74, v55
	v_exp_f32_e32 v76, v56
	v_exp_f32_e32 v78, v57
	v_exp_f32_e32 v94, v58
	v_exp_f32_e32 v73, v4
	v_exp_f32_e32 v69, v5
	v_exp_f32_e32 v71, v6
	v_exp_f32_e32 v75, v7
	v_exp_f32_e32 v77, v8
	v_add_f32_e32 v80, 0, v72
	v_add_f32_e32 v81, 0, v73
	v_exp_f32_e32 v79, v9
	v_add_f32_e32 v80, v68, v80
	v_add_f32_e32 v81, v69, v81
	v_exp_f32_e32 v95, v10
	v_add_f32_e32 v80, v70, v80
	v_add_f32_e32 v81, v71, v81
	v_exp_f32_e32 v96, v59
	v_add_f32_e32 v80, v74, v80
	v_add_f32_e32 v81, v75, v81
	v_exp_f32_e32 v97, v11
	v_add_f32_e32 v80, v76, v80
	v_add_f32_e32 v81, v77, v81
	v_exp_f32_e32 v82, v61
	v_add_f32_e32 v98, v78, v80
	v_add_f32_e32 v99, v79, v81
	v_exp_f32_e32 v80, v60
	v_exp_f32_e32 v81, v12
	v_exp_f32_e32 v83, v13
	v_exp_f32_e32 v84, v62
	v_exp_f32_e32 v85, v14
	v_add_f32_e32 v98, v94, v98
	v_add_f32_e32 v99, v95, v99
	v_exp_f32_e32 v86, v63
	v_exp_f32_e32 v87, v15
	v_add_f32_e32 v98, v96, v98
	v_add_f32_e32 v99, v97, v99
	v_exp_f32_e32 v88, v64
	v_exp_f32_e32 v89, v16
	v_add_f32_e32 v98, v80, v98
	v_add_f32_e32 v99, v81, v99
	v_exp_f32_e32 v90, v65
	v_exp_f32_e32 v91, v17
	v_add_f32_e32 v98, v82, v98
	v_add_f32_e32 v99, v83, v99
	v_exp_f32_e32 v92, v66
	v_exp_f32_e32 v93, v18
	v_add_f32_e32 v98, v84, v98
	v_add_f32_e32 v99, v85, v99
	v_exp_f32_e32 v100, v67
	v_exp_f32_e32 v101, v19
	v_add_f32_e32 v98, v86, v98
	v_add_f32_e32 v99, v87, v99
	s_nop 0
	v_add_f32_e32 v98, v88, v98
	v_add_f32_e32 v99, v89, v99
	s_nop 0
	v_add_f32_e32 v98, v90, v98
	v_add_f32_e32 v99, v91, v99
	s_nop 0
	v_add_f32_e32 v98, v92, v98
	v_add_f32_e32 v99, v93, v99
	s_nop 0
	v_add_f32_e32 v98, v100, v98
	v_add_f32_e32 v99, v101, v99
	s_nop 0
	v_add_f32_e32 v1, v98, v99
	v_cmp_ngt_f32_e32 vcc, s79, v1
	s_cbranch_vccz .LBB0_469
; DI float ex2(float x) { return __builtin_amdgcn_exp2f(x); }
; DI void mla_item(const P& p, char* smem, int b, int hd, int q0, bool samp) {
;     ...
;       if (redo) {
;         float mx = fmaxf(s[0][0], s[1][0]);
; #pragma unroll
;         for (int i = 1; i < 16; ++i) mx = fmaxf(mx, fmaxf(s[0][i], s[1][i]));
;         mx = fmaxf(mx, __shfl_xor(mx, 32));
;         const float up = (kb == 0) ? mx : fmaxf(mx, 0.f);
;         const float alpha = (kb == 0) ? 0.f : ex2(-up);
;         lsum *= alpha;
; #pragma unroll
;         for (int i = 0; i < 16; ++i) { o[0][i] *= alpha; o[1][i] *= alpha; }
;         mrun = (kb == 0) ? mx : mrun + up;
;         ps0 = 0.f; ps1 = 0.f;
; #pragma unroll
;         for (int i = 0; i < 16; ++i) { e[0][i] = ex2(s[0][i] - up); e[1][i] = ex2(s[1][i] - up); ps0 += e[0][i]; ps1 += e[1][i]; }
;       }
;       lsum += ps0 + ps1;
	v_max_f32_e32 v1, v5, v5
	v_max_f32_e32 v2, v53, v53
	v_max_f32_e32 v1, v2, v1
	v_max_f32_e32 v2, v6, v6
	v_max_f32_e32 v68, v54, v54
	v_max_f32_e32 v2, v68, v2
	v_max_f32_e32 v68, v7, v7
	v_max_f32_e32 v69, v55, v55
	v_max3_f32 v1, v52, v4, v1
	v_max_f32_e32 v68, v69, v68
	v_max3_f32 v1, v1, v2, v68
	v_max_f32_e32 v2, v8, v8
	v_max_f32_e32 v68, v56, v56
	v_max_f32_e32 v2, v68, v2
	v_max_f32_e32 v68, v9, v9
	v_max_f32_e32 v69, v57, v57
	v_max_f32_e32 v68, v69, v68
	v_max3_f32 v1, v1, v2, v68
	v_max_f32_e32 v2, v10, v10
	v_max_f32_e32 v68, v58, v58
	v_max_f32_e32 v2, v68, v2
	v_max_f32_e32 v68, v11, v11
	v_max_f32_e32 v69, v59, v59
	v_max_f32_e32 v68, v69, v68
	v_max3_f32 v1, v1, v2, v68
	v_max_f32_e32 v2, v12, v12
	v_max_f32_e32 v68, v60, v60
	v_max_f32_e32 v2, v68, v2
	v_max_f32_e32 v68, v13, v13
	v_max_f32_e32 v69, v61, v61
	v_max_f32_e32 v68, v69, v68
	v_max3_f32 v1, v1, v2, v68
	v_max_f32_e32 v2, v14, v14
	v_max_f32_e32 v68, v62, v62
	v_max_f32_e32 v2, v68, v2
	v_max_f32_e32 v68, v15, v15
	v_max_f32_e32 v69, v63, v63
	v_max_f32_e32 v68, v69, v68
	v_max3_f32 v1, v1, v2, v68
	v_max_f32_e32 v2, v16, v16
	v_max_f32_e32 v68, v64, v64
	v_max_f32_e32 v2, v68, v2
	v_max_f32_e32 v68, v17, v17
	v_max_f32_e32 v69, v65, v65
	v_max_f32_e32 v68, v69, v68
	v_max3_f32 v1, v1, v2, v68
	v_max_f32_e32 v2, v18, v18
	v_max_f32_e32 v68, v66, v66
	v_max_f32_e32 v2, v68, v2
	v_max_f32_e32 v68, v19, v19
	v_max_f32_e32 v69, v67, v67
	v_max_f32_e32 v68, v69, v68
	v_max3_f32 v1, v1, v2, v68
	v_and_b32_e32 v68, 64, v154
	v_xor_b32_e32 v2, 32, v154
	v_add_u32_e32 v68, 64, v68
	v_cmp_lt_i32_e32 vcc, v2, v68
	s_nop 1
	v_cndmask_b32_e32 v2, v154, v2, vcc
	v_lshlrev_b32_e32 v2, 2, v2
	ds_bpermute_b32 v2, v2, v1
	s_waitcnt lgkmcnt(0)
	v_max3_f32 v1, v1, v2, 0
	v_sub_f32_e32 v2, v52, v1
	v_exp_f32_e32 v72, v2
	v_sub_f32_e32 v2, v4, v1
	v_exp_f32_e32 v73, v2
	v_sub_f32_e32 v2, v53, v1
	v_exp_f32_e32 v68, v2
	v_sub_f32_e32 v2, v5, v1
	v_exp_f32_e32 v69, v2
	v_sub_f32_e32 v2, v54, v1
	v_exp_f32_e32 v70, v2
	v_sub_f32_e32 v2, v6, v1
	v_exp_f32_e32 v71, v2
	v_sub_f32_e32 v2, v55, v1
	v_exp_f32_e32 v74, v2
	v_sub_f32_e32 v2, v7, v1
	v_exp_f32_e32 v75, v2
	v_sub_f32_e32 v2, v56, v1
	v_exp_f32_e32 v76, v2
	v_sub_f32_e32 v2, v8, v1
	v_exp_f32_e32 v77, v2
	v_sub_f32_e32 v2, v57, v1
	v_exp_f32_e32 v78, v2
	v_sub_f32_e32 v2, v9, v1
	v_exp_f32_e32 v79, v2
	v_sub_f32_e32 v2, v58, v1
	v_exp_f32_e32 v94, v2
	v_sub_f32_e32 v2, v10, v1
	v_exp_f32_e32 v95, v2
	v_sub_f32_e32 v2, v59, v1
	v_exp_f32_e32 v96, v2
	v_sub_f32_e32 v2, v11, v1
	v_exp_f32_e32 v97, v2
	v_sub_f32_e32 v2, v60, v1
	v_exp_f32_e32 v80, v2
	v_sub_f32_e32 v2, v12, v1
	v_exp_f32_e32 v81, v2
	v_sub_f32_e32 v2, v61, v1
	v_exp_f32_e32 v82, v2
	v_sub_f32_e32 v2, v13, v1
	v_exp_f32_e32 v83, v2
	v_sub_f32_e32 v2, v62, v1
	v_add_f32_e32 v4, 0, v72
	v_add_f32_e32 v5, 0, v73
	v_exp_f32_e32 v84, v2
	v_sub_f32_e32 v2, v14, v1
	v_add_f32_e32 v4, v68, v4
	v_add_f32_e32 v5, v69, v5
	v_exp_f32_e32 v85, v2
	v_sub_f32_e32 v2, v63, v1
	v_add_f32_e32 v4, v70, v4
	v_add_f32_e32 v5, v71, v5
	v_exp_f32_e32 v86, v2
	v_sub_f32_e32 v2, v15, v1
	v_add_f32_e32 v4, v74, v4
	v_add_f32_e32 v5, v75, v5
	v_exp_f32_e32 v87, v2
	v_sub_f32_e32 v2, v64, v1
	v_add_f32_e32 v4, v76, v4
	v_add_f32_e32 v5, v77, v5
	v_exp_f32_e32 v88, v2
	v_sub_f32_e32 v2, v16, v1
	v_add_f32_e32 v4, v78, v4
	v_add_f32_e32 v5, v79, v5
	v_exp_f32_e32 v89, v2
	v_sub_f32_e32 v2, v65, v1
	v_exp_f32_e32 v90, v2
	v_sub_f32_e32 v2, v17, v1
	v_add_f32_e32 v4, v94, v4
	v_add_f32_e32 v5, v95, v5
	v_exp_f32_e32 v91, v2
	v_sub_f32_e32 v2, v66, v1
	v_add_f32_e32 v4, v96, v4
	v_add_f32_e32 v5, v97, v5
	v_exp_f32_e32 v92, v2
	v_sub_f32_e32 v2, v18, v1
	v_add_f32_e32 v4, v80, v4
	v_add_f32_e32 v5, v81, v5
	v_exp_f32_e64 v102, -v1
	v_exp_f32_e32 v93, v2
	v_add_f32_e32 v4, v82, v4
	v_add_f32_e32 v5, v83, v5
	v_sub_f32_e32 v2, v67, v1
	v_sub_f32_e32 v1, v19, v1
	v_add_f32_e32 v4, v84, v4
	v_add_f32_e32 v5, v85, v5
	v_exp_f32_e32 v15, v1
	v_add_f32_e32 v4, v86, v4
	v_add_f32_e32 v5, v87, v5
	v_exp_f32_e32 v100, v2
	v_add_f32_e32 v4, v88, v4
	v_add_f32_e32 v5, v89, v5
	v_mov_b32_e32 v101, v15
	v_add_f32_e32 v4, v90, v4
	v_add_f32_e32 v5, v91, v5
	v_pk_mul_f32 v[34:35], v[34:35], v[102:103] op_sel_hi:[1,0]
	v_add_f32_e32 v12, v92, v4
	v_add_f32_e32 v13, v93, v5
	v_pk_mul_f32 v[32:33], v[32:33], v[102:103] op_sel_hi:[1,0]
	v_pk_mul_f32 v[30:31], v[30:31], v[102:103] op_sel_hi:[1,0]
	v_pk_mul_f32 v[28:29], v[28:29], v[102:103] op_sel_hi:[1,0]
	v_pk_mul_f32 v[26:27], v[26:27], v[102:103] op_sel_hi:[1,0]
	v_pk_mul_f32 v[24:25], v[24:25], v[102:103] op_sel_hi:[1,0]
	v_pk_mul_f32 v[22:23], v[22:23], v[102:103] op_sel_hi:[1,0]
	v_pk_mul_f32 v[20:21], v[20:21], v[102:103] op_sel_hi:[1,0]
	v_mov_b32_e32 v2, v73
	v_mov_b32_e32 v1, v69
	v_mov_b32_e32 v10, v71
	v_mov_b32_e32 v11, v75
	v_mov_b32_e32 v4, v77
	v_mov_b32_e32 v5, v79
	v_mov_b32_e32 v6, v95
	v_mov_b32_e32 v7, v97
	v_mov_b32_e32 v8, v81
	v_mov_b32_e32 v9, v83
	v_add_f32_e32 v98, v100, v12
	v_add_f32_e32 v99, v101, v13
	v_pk_mul_f32 v[50:51], v[50:51], v[102:103] op_sel_hi:[1,0]
	v_pk_mul_f32 v[48:49], v[48:49], v[102:103] op_sel_hi:[1,0]
	v_pk_mul_f32 v[46:47], v[46:47], v[102:103] op_sel_hi:[1,0]
	v_pk_mul_f32 v[44:45], v[44:45], v[102:103] op_sel_hi:[1,0]
	v_pk_mul_f32 v[42:43], v[42:43], v[102:103] op_sel_hi:[1,0]
	v_pk_mul_f32 v[40:41], v[40:41], v[102:103] op_sel_hi:[1,0]
	v_pk_mul_f32 v[38:39], v[38:39], v[102:103] op_sel_hi:[1,0]
	v_pk_mul_f32 v[36:37], v[36:37], v[102:103] op_sel_hi:[1,0]
	v_mul_f32_e32 v161, v161, v102
	v_mov_b32_e32 v12, v85
	v_mov_b32_e32 v13, v87
	v_mov_b32_e32 v14, v89
	v_mov_b32_e32 v17, v91
	v_mov_b32_e32 v16, v93
	s_branch .LBB0_470
